# o57: o54 + loop-top VGPR offset copies (4 v_mov per trip) hoisted into the previous trip's last MFMA window, 6 GEMM loops (in-proj, FF1, FF2)
# speedup vs baseline: 1.0090x; 1.0090x over previous
;     __device__ float mid(int row) const { return rg(row) / ra(row); }
;     __device__ __forceinline__ bool next(int i, Unit& u) const { return map(rank + i * nloc, u); }
;     __device__ __forceinline__ bool next(int i, Unit& u) const { if (i >= __builtin_amdgcn_readfirstlane(tab[0])) return false; u.pm = __builtin_amdgcn_readfirstlane(tab[1 + 2 * i]); u.pn = __builtin_amdgcn_readfirstlane(tab[2 + 2 * i]); return true; }
; #define PG8_STAGE(bufoff, gbase, voff) do { const char* gb_ = (const char*)(gbase); asm volatile("" : "+s"(gb_));     \
;         _Pragma("unroll") for (int _i = 0; _i < 2; ++_i) \
;         __builtin_amdgcn_global_load_lds((const unsigned*)(gb_ + (voff)[_i]), (PG8_LAS unsigned*)(lds + (bufoff) + ldsw + _i * 8192), 16, 0, 0); } while (0)
; #define PG8_LDA(dst, b, h) do { _Pragma("unroll") for (int m = 0; m < 4; ++m) _Pragma("unroll") for (int k = 0; k < 2; ++k) dst[m][k] = *(const PG8_LAS bf16x8*)(lds + PG8_SA(b, h) + aoff + m * 2048 + k * 1024); } while (0)
; template <class Epi, class Sched, bool ALIGN_EPI = false, bool SP2 = false>
; __device__ __forceinline__ void gemm_phase(PG8_LAS unsigned char* lds, const Gemm g, const Sched& S, const Epi& E, int wid0) {
;     ...
;         const bool has_next = S.next(ui + 1, nxt); nxt.ui = ui + 1;
;         if constexpr (Epi::HAS_PRE) E.pre_finish(lds, cur, tid, pq0, pq1, pq2);
;         const char* nA = has_next ? (const char*)g.A + (size_t)nxt.pm * tstepA : cA; const char* nB = has_next ? (const char*)g.Bt + (size_t)nxt.pn * tstep : cB;
; #pragma nounroll
;         for (int t = 0; t < nt; t += 2) {
;             const bool last = (t == nt - 2);
;             const char* a1 = cA + (size_t)(t + 1) * kstep;
;             const char* a2 = last ? nA : cA + (size_t)(t + 2) * kstep; const char* b2 = last ? nB : cB + (size_t)(t + 2) * kstep;
;             const char* a3 = a2 + kstep; const char* b3 = b2 + kstep;
;             if (last && has_next) S.a_ready(nxt);
;             if constexpr (Epi::HAS_MID) { if (t == Epi::MID_T) E.mid(acc, cur, wr, fr); }
;             unsigned vA_[2] = {voffA[0], voffA[1]}, vB_[2] = {voffB[0], voffB[1]};
;             asm volatile("" : "+v"(vA_[0]), "+v"(vA_[1]), "+v"(vB_[0]), "+v"(vB_[1]));
;             if constexpr (SP2) {
;             PG8_LDB(B0, 0, 0); PG8_LDB(B1, 0, 1); PG8_SCHED; PG8_LDA(At, 0, 0); PG8_STAGE(PG8_SA(1, 1), a1 + hstepA, vA_);
.LBB13_355:
	s_or_b64 exec, exec, s[10:11]
	s_and_saveexec_b64 s[10:11], s[4:5]
	s_lshl_b32 s12, s77, 10
	s_and_b32 s12, s12, 0x400
	v_add_u32_e32 v8, s12, v179
	ds_write_b128 v8, v[10:13]
	s_or_b64 exec, exec, s[10:11]
	s_ashr_i32 s47, s46, 31
	s_lshl_b64 s[10:11], s[46:47], 19
	s_add_u32 s50, s33, s10
	s_addc_u32 s51, s60, s11
	s_and_b64 s[10:11], s[0:1], exec
	s_cselect_b32 s47, s51, s3
	s_cselect_b32 s78, s50, s2
	s_ashr_i32 s49, s48, 31
	s_lshl_b64 s[10:11], s[48:49], 19
	s_add_u32 s52, s61, s10
	s_addc_u32 s53, s62, s11
	s_and_b64 s[10:11], s[0:1], exec
	s_cselect_b32 s49, s53, s9
	s_cselect_b32 s79, s52, s8
	s_add_u32 s80, s8, 0x100
	s_waitcnt lgkmcnt(0)
	v_mov_b32_e32 v14, 0
	s_addc_u32 s81, s9, 0
	s_mov_b32 s82, -2
	v_mov_b32_e32 v15, v14
	v_mov_b32_e32 v16, v14
	v_mov_b32_e32 v17, v14
	v_mov_b32_e32 v18, v14
	v_mov_b32_e32 v19, v14
	v_mov_b32_e32 v20, v14
	v_mov_b32_e32 v21, v14
	v_mov_b32_e32 v30, v14
	v_mov_b32_e32 v31, v14
	v_mov_b32_e32 v32, v14
	v_mov_b32_e32 v33, v14
	v_mov_b32_e32 v34, v14
	v_mov_b32_e32 v35, v14
	v_mov_b32_e32 v36, v14
	v_mov_b32_e32 v37, v14
	v_mov_b32_e32 v46, v14
	v_mov_b32_e32 v47, v14
	v_mov_b32_e32 v48, v14
	v_mov_b32_e32 v49, v14
	v_mov_b32_e32 v50, v14
	v_mov_b32_e32 v51, v14
	v_mov_b32_e32 v52, v14
	v_mov_b32_e32 v53, v14
	v_mov_b32_e32 v62, v14
	v_mov_b32_e32 v63, v14
	v_mov_b32_e32 v64, v14
	v_mov_b32_e32 v65, v14
	v_mov_b32_e32 v66, v14
	v_mov_b32_e32 v67, v14
	v_mov_b32_e32 v68, v14
	v_mov_b32_e32 v69, v14
	v_mov_b32_e32 v22, v14
	v_mov_b32_e32 v23, v14
	v_mov_b32_e32 v24, v14
	v_mov_b32_e32 v25, v14
	v_mov_b32_e32 v26, v14
	v_mov_b32_e32 v27, v14
	v_mov_b32_e32 v28, v14
	v_mov_b32_e32 v29, v14
	v_mov_b32_e32 v38, v14
	v_mov_b32_e32 v39, v14
	v_mov_b32_e32 v40, v14
	v_mov_b32_e32 v41, v14
	v_mov_b32_e32 v42, v14
	v_mov_b32_e32 v43, v14
	v_mov_b32_e32 v44, v14
	v_mov_b32_e32 v45, v14
	v_mov_b32_e32 v54, v14
	v_mov_b32_e32 v55, v14
	v_mov_b32_e32 v56, v14
	v_mov_b32_e32 v57, v14
	v_mov_b32_e32 v58, v14
	v_mov_b32_e32 v59, v14
	v_mov_b32_e32 v60, v14
	v_mov_b32_e32 v61, v14
	v_mov_b32_e32 v70, v14
	v_mov_b32_e32 v71, v14
	v_mov_b32_e32 v72, v14
	v_mov_b32_e32 v73, v14
	v_mov_b32_e32 v74, v14
	v_mov_b32_e32 v75, v14
	v_mov_b32_e32 v76, v14
	v_mov_b32_e32 v77, v14
	v_mov_b32_e32 v78, v14
	v_mov_b32_e32 v79, v14
	v_mov_b32_e32 v80, v14
	v_mov_b32_e32 v81, v14
	v_mov_b32_e32 v86, v14
	v_mov_b32_e32 v87, v14
	v_mov_b32_e32 v88, v14
	v_mov_b32_e32 v89, v14
	v_mov_b32_e32 v110, v14
	v_mov_b32_e32 v111, v14
	v_mov_b32_e32 v112, v14
	v_mov_b32_e32 v113, v14
	v_mov_b32_e32 v114, v14
	v_mov_b32_e32 v115, v14
	v_mov_b32_e32 v116, v14
	v_mov_b32_e32 v117, v14
	v_mov_b32_e32 v126, v14
	v_mov_b32_e32 v127, v14
	v_mov_b32_e32 v128, v14
	v_mov_b32_e32 v129, v14
	v_mov_b32_e32 v130, v14
	v_mov_b32_e32 v131, v14
	v_mov_b32_e32 v132, v14
	v_mov_b32_e32 v133, v14
	v_mov_b32_e32 v142, v14
	v_mov_b32_e32 v143, v14
	v_mov_b32_e32 v144, v14
	v_mov_b32_e32 v145, v14
	v_mov_b32_e32 v146, v14
	v_mov_b32_e32 v147, v14
	v_mov_b32_e32 v148, v14
	v_mov_b32_e32 v149, v14
	v_mov_b32_e32 v98, v14
	v_mov_b32_e32 v99, v14
	v_mov_b32_e32 v100, v14
	v_mov_b32_e32 v101, v14
	v_mov_b32_e32 v106, v14
	v_mov_b32_e32 v107, v14
	v_mov_b32_e32 v108, v14
	v_mov_b32_e32 v109, v14
	v_mov_b32_e32 v118, v14
	v_mov_b32_e32 v119, v14
	v_mov_b32_e32 v120, v14
	v_mov_b32_e32 v121, v14
	v_mov_b32_e32 v122, v14
	v_mov_b32_e32 v123, v14
	v_mov_b32_e32 v124, v14
	v_mov_b32_e32 v125, v14
	v_mov_b32_e32 v134, v14
	v_mov_b32_e32 v135, v14
	v_mov_b32_e32 v136, v14
	v_mov_b32_e32 v137, v14
	v_mov_b32_e32 v138, v14
	v_mov_b32_e32 v139, v14
	v_mov_b32_e32 v140, v14
	v_mov_b32_e32 v141, v14
	v_mov_b32_e32 v150, v14
	v_mov_b32_e32 v151, v14
	v_mov_b32_e32 v152, v14
	v_mov_b32_e32 v153, v14
	v_mov_b32_e32 v154, v14
	v_mov_b32_e32 v155, v14
	v_mov_b32_e32 v156, v14
	v_mov_b32_e32 v157, v14
	v_mov_b32_e32 v8, v174
	v_mov_b32_e32 v220, v200
	v_mov_b32_e32 v221, v176
	v_mov_b32_e32 v222, v178
.LBB13_358:
	ds_read_b128 v[82:85], v201
	ds_read_b128 v[90:93], v201 offset:1024
	ds_read_b128 v[94:97], v201 offset:2048
	ds_read_b128 v[102:105], v201 offset:3072
	ds_read_b128 v[158:161], v202
	ds_read_b128 v[162:165], v202 offset:1024
	ds_read_b128 v[166:169], v202 offset:2048
	ds_read_b128 v[170:173], v202 offset:3072
	s_add_u32 s8, s2, 0x100
	s_addc_u32 s9, s3, 0
	s_cmp_eq_u32 s82, 12
	s_cselect_b32 s58, s78, s8
	s_cselect_b32 s59, s47, s9
	s_cselect_b32 s12, s79, s80
	s_cselect_b32 s13, s49, s81
	s_add_u32 s10, s58, 0x80
	s_addc_u32 s11, s59, 0
	s_add_u32 s2, s2, 0x40080
	s_addc_u32 s3, s3, 0
	s_add_i32 m0, s57, 0xc000
	ds_read_b128 v[180:183], v203
	ds_read_b128 v[184:187], v203 offset:1024
	ds_read_b128 v[188:191], v203 offset:2048
	ds_read_b128 v[192:195], v203 offset:3072
	ds_read_b128 v[204:207], v203 offset:4096
	ds_read_b128 v[208:211], v203 offset:5120
	ds_read_b128 v[212:215], v203 offset:6144
	ds_read_b128 v[216:219], v203 offset:7168
	s_nop 0
	global_load_lds_dwordx4 v8, s[2:3]
	s_add_i32 m0, s57, 0xe000
	s_nop 0
	global_load_lds_dwordx4 v221, s[2:3]
	s_waitcnt vmcnt(8)
	s_waitcnt lgkmcnt(0)
	s_barrier
; #define PG8_STAGE(bufoff, gbase, voff) do { const char* gb_ = (const char*)(gbase); asm volatile("" : "+s"(gb_));     \
;         _Pragma("unroll") for (int _i = 0; _i < 2; ++_i) \
;         __builtin_amdgcn_global_load_lds((const unsigned*)(gb_ + (voff)[_i]), (PG8_LAS unsigned*)(lds + (bufoff) + ldsw + _i * 8192), 16, 0, 0); } while (0)
; #define PG8_LDA(dst, b, h) do { _Pragma("unroll") for (int m = 0; m < 4; ++m) _Pragma("unroll") for (int k = 0; k < 2; ++k) dst[m][k] = *(const PG8_LAS bf16x8*)(lds + PG8_SA(b, h) + aoff + m * 2048 + k * 1024); } while (0)
; #define PG8_LDB(dst, b, h) do { _Pragma("unroll") for (int n = 0; n < 2; ++n) _Pragma("unroll") for (int k = 0; k < 2; ++k) dst[n][k] = *(const PG8_LAS bf16x8*)(lds + PG8_SB(b, h) + boff + n * 2048 + k * 1024); } while (0)
; #define PG8_MMA(ai, bj, At, Bt) do { __builtin_amdgcn_s_setprio(1); _Pragma("unroll") for (int m = 0; m < 4; ++m) _Pragma("unroll") for (int n = 0; n < 2; ++n) _Pragma("unroll") for (int k = 0; k < 2; ++k) \
;         acc[ai][bj][m][n] = __builtin_amdgcn_mfma_f32_16x16x32_bf16(Bt[n][k], At[m][k], acc[ai][bj][m][n], 0, 0, 0); __builtin_amdgcn_s_setprio(0); } while (0)
; #define PG8_WAIT_V(n) asm volatile("s_waitcnt vmcnt(" #n ")" ::: "memory")
; #define PG8_WAIT_L(n) asm volatile("s_waitcnt lgkmcnt(" #n ")" ::: "memory")
; #define PG8_BAR __builtin_amdgcn_s_barrier()
; #define PG8_SCHED __builtin_amdgcn_sched_barrier(0)
; template <class Epi, class Sched, bool ALIGN_EPI = false, bool SP2 = false>
; __device__ __forceinline__ void gemm_phase(PG8_LAS unsigned char* lds, const Gemm g, const Sched& S, const Epi& E, int wid0) {
;     ...
;             PG8_LDB(B0, 0, 0); PG8_LDB(B1, 0, 1); PG8_SCHED; PG8_LDA(At, 0, 0); PG8_STAGE(PG8_SA(1, 1), a1 + hstepA, vA_);
;             PG8_WAIT_V(8); PG8_WAIT_L(0); PG8_BAR; PG8_MMA(0, 0, At, B0); PG8_MMA(0, 1, At, B1); PG8_BAR; PG8_SCHED;
;             PG8_LDA(At, 0, 1); PG8_STAGE(PG8_SB(0, 0), b2, vB_); PG8_STAGE(PG8_SB(0, 1), b2 + hstep, vB_); PG8_STAGE(PG8_SA(0, 0), a2, vA_);
;             PG8_WAIT_V(8); PG8_WAIT_L(0); PG8_BAR; PG8_MMA(1, 0, At, B0); PG8_MMA(1, 1, At, B1); PG8_BAR; PG8_SCHED;
	s_setprio 1
	s_waitcnt lgkmcnt(0)
	v_mfma_f32_16x16x32_bf16 v[154:157], v[82:85], v[180:183], v[154:157]
	v_mfma_f32_16x16x32_bf16 v[150:153], v[94:97], v[180:183], v[150:153]
	v_mfma_f32_16x16x32_bf16 v[138:141], v[82:85], v[188:191], v[138:141]
	v_mfma_f32_16x16x32_bf16 v[134:137], v[94:97], v[188:191], v[134:137]
	v_mfma_f32_16x16x32_bf16 v[122:125], v[82:85], v[204:207], v[122:125]
	v_mfma_f32_16x16x32_bf16 v[118:121], v[94:97], v[204:207], v[118:121]
	v_mfma_f32_16x16x32_bf16 v[106:109], v[82:85], v[212:215], v[106:109]
	v_mfma_f32_16x16x32_bf16 v[98:101], v[94:97], v[212:215], v[98:101]
	v_mfma_f32_16x16x32_bf16 v[154:157], v[90:93], v[184:187], v[154:157]
	v_mfma_f32_16x16x32_bf16 v[150:153], v[102:105], v[184:187], v[150:153]
	v_mfma_f32_16x16x32_bf16 v[138:141], v[90:93], v[192:195], v[138:141]
	v_mfma_f32_16x16x32_bf16 v[134:137], v[102:105], v[192:195], v[134:137]
	v_mfma_f32_16x16x32_bf16 v[122:125], v[90:93], v[208:211], v[122:125]
	v_mfma_f32_16x16x32_bf16 v[118:121], v[102:105], v[208:211], v[118:121]
	v_mfma_f32_16x16x32_bf16 v[106:109], v[90:93], v[216:219], v[106:109]
	v_mfma_f32_16x16x32_bf16 v[98:101], v[102:105], v[216:219], v[98:101]
	s_setprio 0
	s_setprio 1
	v_mfma_f32_16x16x32_bf16 v[146:149], v[158:161], v[180:183], v[146:149]
	v_mfma_f32_16x16x32_bf16 v[142:145], v[166:169], v[180:183], v[142:145]
	v_mfma_f32_16x16x32_bf16 v[130:133], v[158:161], v[188:191], v[130:133]
	v_mfma_f32_16x16x32_bf16 v[126:129], v[166:169], v[188:191], v[126:129]
	v_mfma_f32_16x16x32_bf16 v[114:117], v[158:161], v[204:207], v[114:117]
	v_mfma_f32_16x16x32_bf16 v[110:113], v[166:169], v[204:207], v[110:113]
	v_mfma_f32_16x16x32_bf16 v[86:89], v[158:161], v[212:215], v[86:89]
	v_mfma_f32_16x16x32_bf16 v[78:81], v[166:169], v[212:215], v[78:81]
	v_mfma_f32_16x16x32_bf16 v[146:149], v[162:165], v[184:187], v[146:149]
	v_mfma_f32_16x16x32_bf16 v[142:145], v[170:173], v[184:187], v[142:145]
	v_mfma_f32_16x16x32_bf16 v[130:133], v[162:165], v[192:195], v[130:133]
	v_mfma_f32_16x16x32_bf16 v[126:129], v[170:173], v[192:195], v[126:129]
	v_mfma_f32_16x16x32_bf16 v[114:117], v[162:165], v[208:211], v[114:117]
	v_mfma_f32_16x16x32_bf16 v[110:113], v[170:173], v[208:211], v[110:113]
	v_mfma_f32_16x16x32_bf16 v[86:89], v[162:165], v[216:219], v[86:89]
	v_mfma_f32_16x16x32_bf16 v[78:81], v[170:173], v[216:219], v[78:81]
	s_setprio 0
	s_barrier
	s_add_i32 s83, s74, s55
	s_mov_b64 s[2:3], s[12:13]
	s_mov_b32 m0, s83
	ds_read_b128 v[180:183], v203 offset:16384
	ds_read_b128 v[184:187], v203 offset:17408
	ds_read_b128 v[188:191], v203 offset:18432
	ds_read_b128 v[192:195], v203 offset:19456
	ds_read_b128 v[204:207], v203 offset:20480
	ds_read_b128 v[208:211], v203 offset:21504
	ds_read_b128 v[212:215], v203 offset:22528
	ds_read_b128 v[216:219], v203 offset:23552
	s_nop 0
	global_load_lds_dwordx4 v220, s[2:3]
	s_add_i32 m0, s83, 0x2000
	s_nop 0
	global_load_lds_dwordx4 v222, s[2:3]
	s_add_u32 s2, s12, 0x40000
	s_addc_u32 s3, s13, 0
	s_add_i32 s83, s75, s55
	s_mov_b32 m0, s83
	s_nop 0
	global_load_lds_dwordx4 v220, s[2:3]
	s_add_i32 m0, s83, 0x2000
	s_nop 0
	global_load_lds_dwordx4 v222, s[2:3]
	s_mov_b64 s[2:3], s[58:59]
	s_mov_b32 m0, s57
	s_nop 0
	global_load_lds_dwordx4 v8, s[2:3]
	s_mov_b32 m0, s63
	s_nop 0
	global_load_lds_dwordx4 v221, s[2:3]
	s_waitcnt vmcnt(8)
	s_waitcnt lgkmcnt(0)
	s_barrier
	s_setprio 1
	s_waitcnt lgkmcnt(0)
	v_mfma_f32_16x16x32_bf16 v[74:77], v[82:85], v[180:183], v[74:77]
	v_mfma_f32_16x16x32_bf16 v[70:73], v[94:97], v[180:183], v[70:73]
	v_mfma_f32_16x16x32_bf16 v[58:61], v[82:85], v[188:191], v[58:61]
	v_mfma_f32_16x16x32_bf16 v[54:57], v[94:97], v[188:191], v[54:57]
	v_mfma_f32_16x16x32_bf16 v[42:45], v[82:85], v[204:207], v[42:45]
	v_mfma_f32_16x16x32_bf16 v[38:41], v[94:97], v[204:207], v[38:41]
	v_mfma_f32_16x16x32_bf16 v[26:29], v[82:85], v[212:215], v[26:29]
	v_mfma_f32_16x16x32_bf16 v[22:25], v[94:97], v[212:215], v[22:25]
	v_mfma_f32_16x16x32_bf16 v[74:77], v[90:93], v[184:187], v[74:77]
	v_mfma_f32_16x16x32_bf16 v[70:73], v[102:105], v[184:187], v[70:73]
	v_mfma_f32_16x16x32_bf16 v[58:61], v[90:93], v[192:195], v[58:61]
	v_mfma_f32_16x16x32_bf16 v[54:57], v[102:105], v[192:195], v[54:57]
	v_mfma_f32_16x16x32_bf16 v[42:45], v[90:93], v[208:211], v[42:45]
	v_mfma_f32_16x16x32_bf16 v[38:41], v[102:105], v[208:211], v[38:41]
	v_mfma_f32_16x16x32_bf16 v[26:29], v[90:93], v[216:219], v[26:29]
	v_mfma_f32_16x16x32_bf16 v[22:25], v[102:105], v[216:219], v[22:25]
	s_setprio 0
	s_setprio 1
	v_mfma_f32_16x16x32_bf16 v[66:69], v[158:161], v[180:183], v[66:69]
	v_mfma_f32_16x16x32_bf16 v[62:65], v[166:169], v[180:183], v[62:65]
	v_mfma_f32_16x16x32_bf16 v[50:53], v[158:161], v[188:191], v[50:53]
	v_mfma_f32_16x16x32_bf16 v[46:49], v[166:169], v[188:191], v[46:49]
	v_mfma_f32_16x16x32_bf16 v[34:37], v[158:161], v[204:207], v[34:37]
	v_mfma_f32_16x16x32_bf16 v[30:33], v[166:169], v[204:207], v[30:33]
	v_mfma_f32_16x16x32_bf16 v[18:21], v[158:161], v[212:215], v[18:21]
	v_mfma_f32_16x16x32_bf16 v[14:17], v[166:169], v[212:215], v[14:17]
	v_mfma_f32_16x16x32_bf16 v[66:69], v[162:165], v[184:187], v[66:69]
	v_mfma_f32_16x16x32_bf16 v[62:65], v[170:173], v[184:187], v[62:65]
	v_mfma_f32_16x16x32_bf16 v[50:53], v[162:165], v[192:195], v[50:53]
	v_mfma_f32_16x16x32_bf16 v[46:49], v[170:173], v[192:195], v[46:49]
	v_mfma_f32_16x16x32_bf16 v[34:37], v[162:165], v[208:211], v[34:37]
	v_mfma_f32_16x16x32_bf16 v[30:33], v[170:173], v[208:211], v[30:33]
	v_mfma_f32_16x16x32_bf16 v[18:21], v[162:165], v[216:219], v[18:21]
	v_mfma_f32_16x16x32_bf16 v[14:17], v[170:173], v[216:219], v[14:17]
	s_setprio 0
	s_barrier
; #define PG8_STAGE(bufoff, gbase, voff) do { const char* gb_ = (const char*)(gbase); asm volatile("" : "+s"(gb_));     \
;         _Pragma("unroll") for (int _i = 0; _i < 2; ++_i) \
;         __builtin_amdgcn_global_load_lds((const unsigned*)(gb_ + (voff)[_i]), (PG8_LAS unsigned*)(lds + (bufoff) + ldsw + _i * 8192), 16, 0, 0); } while (0)
; #define PG8_LDA(dst, b, h) do { _Pragma("unroll") for (int m = 0; m < 4; ++m) _Pragma("unroll") for (int k = 0; k < 2; ++k) dst[m][k] = *(const PG8_LAS bf16x8*)(lds + PG8_SA(b, h) + aoff + m * 2048 + k * 1024); } while (0)
; #define PG8_LDB(dst, b, h) do { _Pragma("unroll") for (int n = 0; n < 2; ++n) _Pragma("unroll") for (int k = 0; k < 2; ++k) dst[n][k] = *(const PG8_LAS bf16x8*)(lds + PG8_SB(b, h) + boff + n * 2048 + k * 1024); } while (0)
; #define PG8_MMA(ai, bj, At, Bt) do { __builtin_amdgcn_s_setprio(1); _Pragma("unroll") for (int m = 0; m < 4; ++m) _Pragma("unroll") for (int n = 0; n < 2; ++n) _Pragma("unroll") for (int k = 0; k < 2; ++k) \
;         acc[ai][bj][m][n] = __builtin_amdgcn_mfma_f32_16x16x32_bf16(Bt[n][k], At[m][k], acc[ai][bj][m][n], 0, 0, 0); __builtin_amdgcn_s_setprio(0); } while (0)
; #define PG8_WAIT_V(n) asm volatile("s_waitcnt vmcnt(" #n ")" ::: "memory")
; #define PG8_WAIT_L(n) asm volatile("s_waitcnt lgkmcnt(" #n ")" ::: "memory")
; #define PG8_BAR __builtin_amdgcn_s_barrier()
; #define PG8_SCHED __builtin_amdgcn_sched_barrier(0)
; template <class Epi, class Sched, bool ALIGN_EPI = false, bool SP2 = false>
; __device__ __forceinline__ void gemm_phase(PG8_LAS unsigned char* lds, const Gemm g, const Sched& S, const Epi& E, int wid0) {
;     ...
;             PG8_LDB(B0, 1, 0); PG8_LDB(B1, 1, 1); PG8_SCHED; PG8_LDA(At, 1, 0); PG8_STAGE(PG8_SA(0, 1), a2 + hstepA, vA_);
;             PG8_WAIT_V(8); PG8_WAIT_L(0); PG8_BAR; PG8_MMA(0, 0, At, B0); PG8_MMA(0, 1, At, B1); PG8_BAR; PG8_SCHED;
;             PG8_LDA(At, 1, 1); PG8_STAGE(PG8_SB(1, 0), b3, vB_); PG8_STAGE(PG8_SB(1, 1), b3 + hstep, vB_); PG8_STAGE(PG8_SA(1, 0), a3, vA_);
;             PG8_WAIT_V(8); PG8_WAIT_L(0); PG8_BAR; PG8_MMA(1, 0, At, B0); PG8_MMA(1, 1, At, B1); PG8_BAR; PG8_SCHED;
	s_add_i32 s83, 0, 0x18000
	s_add_i32 s84, 0, 0x1c000
	v_add_u32_e32 v102, s83, v175
	v_add_u32_e32 v170, s84, v175
	ds_read_b128 v[82:85], v102
	ds_read_b128 v[90:93], v102 offset:1024
	ds_read_b128 v[94:97], v102 offset:2048
	ds_read_b128 v[102:105], v102 offset:3072
	ds_read_b128 v[158:161], v170
	ds_read_b128 v[162:165], v170 offset:1024
	ds_read_b128 v[166:169], v170 offset:2048
	ds_read_b128 v[170:173], v170 offset:3072
	s_add_u32 s2, s58, 0x40000
	s_addc_u32 s3, s59, 0
	s_mov_b32 m0, s64
	ds_read_b128 v[180:183], v203 offset:32768
	ds_read_b128 v[184:187], v203 offset:33792
	ds_read_b128 v[188:191], v203 offset:34816
	ds_read_b128 v[192:195], v203 offset:35840
	ds_read_b128 v[204:207], v203 offset:36864
	ds_read_b128 v[208:211], v203 offset:37888
	ds_read_b128 v[212:215], v203 offset:38912
	ds_read_b128 v[216:219], v203 offset:39936
	s_nop 0
	global_load_lds_dwordx4 v8, s[2:3]
	s_mov_b32 m0, s65
	s_nop 0
	global_load_lds_dwordx4 v221, s[2:3]
	s_waitcnt vmcnt(8)
	s_waitcnt lgkmcnt(0)
	s_barrier
	s_setprio 1
	s_waitcnt lgkmcnt(0)
	v_mfma_f32_16x16x32_bf16 v[154:157], v[82:85], v[180:183], v[154:157]
	v_mfma_f32_16x16x32_bf16 v[150:153], v[94:97], v[180:183], v[150:153]
	v_mfma_f32_16x16x32_bf16 v[138:141], v[82:85], v[188:191], v[138:141]
	v_mfma_f32_16x16x32_bf16 v[134:137], v[94:97], v[188:191], v[134:137]
	v_mfma_f32_16x16x32_bf16 v[122:125], v[82:85], v[204:207], v[122:125]
	v_mfma_f32_16x16x32_bf16 v[118:121], v[94:97], v[204:207], v[118:121]
	v_mfma_f32_16x16x32_bf16 v[106:109], v[82:85], v[212:215], v[106:109]
	v_mfma_f32_16x16x32_bf16 v[98:101], v[94:97], v[212:215], v[98:101]
	v_mfma_f32_16x16x32_bf16 v[154:157], v[90:93], v[184:187], v[154:157]
	v_mfma_f32_16x16x32_bf16 v[150:153], v[102:105], v[184:187], v[150:153]
	v_mfma_f32_16x16x32_bf16 v[138:141], v[90:93], v[192:195], v[138:141]
	v_mfma_f32_16x16x32_bf16 v[134:137], v[102:105], v[192:195], v[134:137]
	v_mfma_f32_16x16x32_bf16 v[122:125], v[90:93], v[208:211], v[122:125]
	v_mfma_f32_16x16x32_bf16 v[118:121], v[102:105], v[208:211], v[118:121]
	v_mfma_f32_16x16x32_bf16 v[106:109], v[90:93], v[216:219], v[106:109]
	v_mfma_f32_16x16x32_bf16 v[98:101], v[102:105], v[216:219], v[98:101]
	s_setprio 0
	s_setprio 1
	v_mfma_f32_16x16x32_bf16 v[146:149], v[158:161], v[180:183], v[146:149]
	v_mfma_f32_16x16x32_bf16 v[142:145], v[166:169], v[180:183], v[142:145]
	v_mfma_f32_16x16x32_bf16 v[130:133], v[158:161], v[188:191], v[130:133]
	v_mfma_f32_16x16x32_bf16 v[126:129], v[166:169], v[188:191], v[126:129]
	v_mfma_f32_16x16x32_bf16 v[114:117], v[158:161], v[204:207], v[114:117]
	v_mfma_f32_16x16x32_bf16 v[110:113], v[166:169], v[204:207], v[110:113]
	v_mfma_f32_16x16x32_bf16 v[86:89], v[158:161], v[212:215], v[86:89]
	v_mfma_f32_16x16x32_bf16 v[78:81], v[166:169], v[212:215], v[78:81]
	v_mfma_f32_16x16x32_bf16 v[146:149], v[162:165], v[184:187], v[146:149]
	v_mfma_f32_16x16x32_bf16 v[142:145], v[170:173], v[184:187], v[142:145]
	v_mfma_f32_16x16x32_bf16 v[130:133], v[162:165], v[192:195], v[130:133]
	v_mfma_f32_16x16x32_bf16 v[126:129], v[170:173], v[192:195], v[126:129]
	v_mfma_f32_16x16x32_bf16 v[114:117], v[162:165], v[208:211], v[114:117]
	v_mfma_f32_16x16x32_bf16 v[110:113], v[170:173], v[208:211], v[110:113]
	v_mfma_f32_16x16x32_bf16 v[86:89], v[162:165], v[216:219], v[86:89]
	v_mfma_f32_16x16x32_bf16 v[78:81], v[170:173], v[216:219], v[78:81]
	s_setprio 0
	s_barrier
	s_add_u32 s2, s12, 0x80
	s_addc_u32 s3, s13, 0
	s_add_i32 s58, s83, s55
	s_mov_b32 m0, s58
	ds_read_b128 v[180:183], v203 offset:49152
	ds_read_b128 v[184:187], v203 offset:50176
	ds_read_b128 v[188:191], v203 offset:51200
	ds_read_b128 v[192:195], v203 offset:52224
	ds_read_b128 v[204:207], v203 offset:53248
	ds_read_b128 v[208:211], v203 offset:54272
	ds_read_b128 v[212:215], v203 offset:55296
	ds_read_b128 v[216:219], v203 offset:56320
	s_nop 0
	global_load_lds_dwordx4 v220, s[2:3]
	s_add_i32 m0, s58, 0x2000
	s_nop 0
	global_load_lds_dwordx4 v222, s[2:3]
	s_add_u32 s2, s12, 0x40080
	s_addc_u32 s3, s13, 0
	s_add_i32 s12, s84, s55
	s_mov_b32 m0, s12
	s_nop 0
	global_load_lds_dwordx4 v220, s[2:3]
	s_add_i32 m0, s12, 0x2000
	s_nop 0
	global_load_lds_dwordx4 v222, s[2:3]
	s_mov_b32 m0, s68
	s_nop 0
	global_load_lds_dwordx4 v8, s[10:11]
	s_mov_b32 m0, s69
	s_nop 0
	global_load_lds_dwordx4 v221, s[10:11]
	s_waitcnt vmcnt(8)
	s_waitcnt lgkmcnt(0)
	s_barrier
	s_setprio 1
	s_waitcnt lgkmcnt(0)
	v_mfma_f32_16x16x32_bf16 v[74:77], v[82:85], v[180:183], v[74:77]
	v_mfma_f32_16x16x32_bf16 v[70:73], v[94:97], v[180:183], v[70:73]
	v_mfma_f32_16x16x32_bf16 v[58:61], v[82:85], v[188:191], v[58:61]
	v_mfma_f32_16x16x32_bf16 v[54:57], v[94:97], v[188:191], v[54:57]
	v_mfma_f32_16x16x32_bf16 v[42:45], v[82:85], v[204:207], v[42:45]
	v_mfma_f32_16x16x32_bf16 v[38:41], v[94:97], v[204:207], v[38:41]
	v_mfma_f32_16x16x32_bf16 v[26:29], v[82:85], v[212:215], v[26:29]
	v_mfma_f32_16x16x32_bf16 v[22:25], v[94:97], v[212:215], v[22:25]
	v_mfma_f32_16x16x32_bf16 v[74:77], v[90:93], v[184:187], v[74:77]
	v_mfma_f32_16x16x32_bf16 v[70:73], v[102:105], v[184:187], v[70:73]
	v_mfma_f32_16x16x32_bf16 v[58:61], v[90:93], v[192:195], v[58:61]
	v_mfma_f32_16x16x32_bf16 v[54:57], v[102:105], v[192:195], v[54:57]
	v_mfma_f32_16x16x32_bf16 v[42:45], v[90:93], v[208:211], v[42:45]
	v_mfma_f32_16x16x32_bf16 v[38:41], v[102:105], v[208:211], v[38:41]
	v_mfma_f32_16x16x32_bf16 v[26:29], v[90:93], v[216:219], v[26:29]
	v_mfma_f32_16x16x32_bf16 v[22:25], v[102:105], v[216:219], v[22:25]
	s_setprio 0
	s_setprio 1
	v_mfma_f32_16x16x32_bf16 v[66:69], v[158:161], v[180:183], v[66:69]
	v_mfma_f32_16x16x32_bf16 v[62:65], v[166:169], v[180:183], v[62:65]
	v_mfma_f32_16x16x32_bf16 v[50:53], v[158:161], v[188:191], v[50:53]
	v_mfma_f32_16x16x32_bf16 v[46:49], v[166:169], v[188:191], v[46:49]
	v_mfma_f32_16x16x32_bf16 v[34:37], v[158:161], v[204:207], v[34:37]
	v_mfma_f32_16x16x32_bf16 v[30:33], v[166:169], v[204:207], v[30:33]
	v_mfma_f32_16x16x32_bf16 v[18:21], v[158:161], v[212:215], v[18:21]
	v_mfma_f32_16x16x32_bf16 v[14:17], v[166:169], v[212:215], v[14:17]
	v_mfma_f32_16x16x32_bf16 v[66:69], v[162:165], v[184:187], v[66:69]
	v_mfma_f32_16x16x32_bf16 v[62:65], v[170:173], v[184:187], v[62:65]
	v_mfma_f32_16x16x32_bf16 v[50:53], v[162:165], v[192:195], v[50:53]
	v_mfma_f32_16x16x32_bf16 v[46:49], v[170:173], v[192:195], v[46:49]
	s_add_i32 s82, s82, 2
	s_add_u32 s80, s80, 0x100
	s_addc_u32 s81, s81, 0
	s_cmp_gt_u32 s82, 13
	s_mov_b64 s[2:3], s[8:9]
	v_mov_b32_e32 v8, v174
	v_mov_b32_e32 v220, v200
	v_mov_b32_e32 v221, v176
	v_mov_b32_e32 v222, v178
	v_mfma_f32_16x16x32_bf16 v[34:37], v[162:165], v[208:211], v[34:37]
	v_mfma_f32_16x16x32_bf16 v[30:33], v[170:173], v[208:211], v[30:33]
	v_mfma_f32_16x16x32_bf16 v[18:21], v[162:165], v[216:219], v[18:21]
	v_mfma_f32_16x16x32_bf16 v[14:17], v[170:173], v[216:219], v[14:17]
	s_setprio 0
	s_barrier
	s_cbranch_scc0 .LBB13_358
	s_and_b64 vcc, exec, s[42:43]
	s_cbranch_vccz .LBB13_361
	s_barrier

;     __device__ float mid(int row) const { return rg(row) / ra(row); }
;     __device__ __forceinline__ bool next(int i, Unit& u) const { return map(rank + i * nloc, u); }
;     __device__ __forceinline__ bool next(int i, Unit& u) const { if (i >= __builtin_amdgcn_readfirstlane(tab[0])) return false; u.pm = __builtin_amdgcn_readfirstlane(tab[1 + 2 * i]); u.pn = __builtin_amdgcn_readfirstlane(tab[2 + 2 * i]); return true; }
; #define PG8_STAGE(bufoff, gbase, voff) do { const char* gb_ = (const char*)(gbase); asm volatile("" : "+s"(gb_));     \
;         _Pragma("unroll") for (int _i = 0; _i < 2; ++_i) \
;         __builtin_amdgcn_global_load_lds((const unsigned*)(gb_ + (voff)[_i]), (PG8_LAS unsigned*)(lds + (bufoff) + ldsw + _i * 8192), 16, 0, 0); } while (0)
; #define PG8_LDA(dst, b, h) do { _Pragma("unroll") for (int m = 0; m < 4; ++m) _Pragma("unroll") for (int k = 0; k < 2; ++k) dst[m][k] = *(const PG8_LAS bf16x8*)(lds + PG8_SA(b, h) + aoff + m * 2048 + k * 1024); } while (0)
; template <class Epi, class Sched, bool ALIGN_EPI = false, bool SP2 = false>
; __device__ __forceinline__ void gemm_phase(PG8_LAS unsigned char* lds, const Gemm g, const Sched& S, const Epi& E, int wid0) {
;     ...
;         const bool has_next = S.next(ui + 1, nxt); nxt.ui = ui + 1;
;         if constexpr (Epi::HAS_PRE) E.pre_finish(lds, cur, tid, pq0, pq1, pq2);
;         const char* nA = has_next ? (const char*)g.A + (size_t)nxt.pm * tstepA : cA; const char* nB = has_next ? (const char*)g.Bt + (size_t)nxt.pn * tstep : cB;
; #pragma nounroll
;         for (int t = 0; t < nt; t += 2) {
;             const bool last = (t == nt - 2);
;             const char* a1 = cA + (size_t)(t + 1) * kstep;
;             const char* a2 = last ? nA : cA + (size_t)(t + 2) * kstep; const char* b2 = last ? nB : cB + (size_t)(t + 2) * kstep;
;             const char* a3 = a2 + kstep; const char* b3 = b2 + kstep;
;             if (last && has_next) S.a_ready(nxt);
;             if constexpr (Epi::HAS_MID) { if (t == Epi::MID_T) E.mid(acc, cur, wr, fr); }
;             unsigned vA_[2] = {voffA[0], voffA[1]}, vB_[2] = {voffB[0], voffB[1]};
;             asm volatile("" : "+v"(vA_[0]), "+v"(vA_[1]), "+v"(vB_[0]), "+v"(vB_[1]));
;             if constexpr (SP2) {
;             PG8_LDB(B0, 0, 0); PG8_LDB(B1, 0, 1); PG8_SCHED; PG8_LDA(At, 0, 0); PG8_STAGE(PG8_SA(1, 1), a1 + hstepA, vA_);
.LBB13_1071:
	s_or_b64 exec, exec, s[22:23]
	s_and_saveexec_b64 s[22:23], s[4:5]
	s_lshl_b32 s19, s56, 10
	s_and_b32 s19, s19, 0x400
	v_add_u32_e32 v14, s19, v161
	ds_write_b128 v14, v[10:13]
	s_or_b64 exec, exec, s[22:23]
	s_ashr_i32 s19, s18, 31
	s_lshl_b64 s[22:23], s[18:19], 19
	s_add_u32 s22, s33, s22
	s_addc_u32 s23, s42, s23
	s_and_b64 s[24:25], s[30:31], exec
	s_cselect_b32 s19, s23, s9
	s_cselect_b32 s57, s22, s8
	s_ashr_i32 s21, s20, 31
	s_lshl_b64 s[24:25], s[20:21], 19
	s_add_u32 s24, s43, s24
	s_addc_u32 s25, s44, s25
	s_and_b64 s[36:37], s[30:31], exec
	s_cselect_b32 s21, s25, s35
	s_cselect_b32 s58, s24, s34
	s_add_u32 s59, s34, 0x100
	v_mov_b32_e32 v14, 0
	s_addc_u32 s60, s35, 0
	s_mov_b32 s61, -2
	s_waitcnt lgkmcnt(0)
	v_mov_b32_e32 v15, v14
	v_mov_b32_e32 v16, v14
	v_mov_b32_e32 v17, v14
	v_mov_b32_e32 v18, v14
	v_mov_b32_e32 v19, v14
	v_mov_b32_e32 v20, v14
	v_mov_b32_e32 v21, v14
	v_mov_b32_e32 v30, v14
	v_mov_b32_e32 v31, v14
	v_mov_b32_e32 v32, v14
	v_mov_b32_e32 v33, v14
	v_mov_b32_e32 v34, v14
	v_mov_b32_e32 v35, v14
	v_mov_b32_e32 v36, v14
	v_mov_b32_e32 v37, v14
	v_mov_b32_e32 v46, v14
	v_mov_b32_e32 v47, v14
	v_mov_b32_e32 v48, v14
	v_mov_b32_e32 v49, v14
	v_mov_b32_e32 v50, v14
	v_mov_b32_e32 v51, v14
	v_mov_b32_e32 v52, v14
	v_mov_b32_e32 v53, v14
	v_mov_b32_e32 v62, v14
	v_mov_b32_e32 v63, v14
	v_mov_b32_e32 v64, v14
	v_mov_b32_e32 v65, v14
	v_mov_b32_e32 v66, v14
	v_mov_b32_e32 v67, v14
	v_mov_b32_e32 v68, v14
	v_mov_b32_e32 v69, v14
	v_mov_b32_e32 v22, v14
	v_mov_b32_e32 v23, v14
	v_mov_b32_e32 v24, v14
	v_mov_b32_e32 v25, v14
	v_mov_b32_e32 v26, v14
	v_mov_b32_e32 v27, v14
	v_mov_b32_e32 v28, v14
	v_mov_b32_e32 v29, v14
	v_mov_b32_e32 v38, v14
	v_mov_b32_e32 v39, v14
	v_mov_b32_e32 v40, v14
	v_mov_b32_e32 v41, v14
	v_mov_b32_e32 v42, v14
	v_mov_b32_e32 v43, v14
	v_mov_b32_e32 v44, v14
	v_mov_b32_e32 v45, v14
	v_mov_b32_e32 v54, v14
	v_mov_b32_e32 v55, v14
	v_mov_b32_e32 v56, v14
	v_mov_b32_e32 v57, v14
	v_mov_b32_e32 v58, v14
	v_mov_b32_e32 v59, v14
	v_mov_b32_e32 v60, v14
	v_mov_b32_e32 v61, v14
	v_mov_b32_e32 v70, v14
	v_mov_b32_e32 v71, v14
	v_mov_b32_e32 v72, v14
	v_mov_b32_e32 v73, v14
	v_mov_b32_e32 v74, v14
	v_mov_b32_e32 v75, v14
	v_mov_b32_e32 v76, v14
	v_mov_b32_e32 v77, v14
	v_mov_b32_e32 v78, v14
	v_mov_b32_e32 v79, v14
	v_mov_b32_e32 v80, v14
	v_mov_b32_e32 v81, v14
	v_mov_b32_e32 v82, v14
	v_mov_b32_e32 v83, v14
	v_mov_b32_e32 v84, v14
	v_mov_b32_e32 v85, v14
	v_mov_b32_e32 v94, v14
	v_mov_b32_e32 v95, v14
	v_mov_b32_e32 v96, v14
	v_mov_b32_e32 v97, v14
	v_mov_b32_e32 v98, v14
	v_mov_b32_e32 v99, v14
	v_mov_b32_e32 v100, v14
	v_mov_b32_e32 v101, v14
	v_mov_b32_e32 v110, v14
	v_mov_b32_e32 v111, v14
	v_mov_b32_e32 v112, v14
	v_mov_b32_e32 v113, v14
	v_mov_b32_e32 v114, v14
	v_mov_b32_e32 v115, v14
	v_mov_b32_e32 v116, v14
	v_mov_b32_e32 v117, v14
	v_mov_b32_e32 v126, v14
	v_mov_b32_e32 v127, v14
	v_mov_b32_e32 v128, v14
	v_mov_b32_e32 v129, v14
	v_mov_b32_e32 v130, v14
	v_mov_b32_e32 v131, v14
	v_mov_b32_e32 v132, v14
	v_mov_b32_e32 v133, v14
	v_mov_b32_e32 v86, v14
	v_mov_b32_e32 v87, v14
	v_mov_b32_e32 v88, v14
	v_mov_b32_e32 v89, v14
	v_mov_b32_e32 v90, v14
	v_mov_b32_e32 v91, v14
	v_mov_b32_e32 v92, v14
	v_mov_b32_e32 v93, v14
	v_mov_b32_e32 v102, v14
	v_mov_b32_e32 v103, v14
	v_mov_b32_e32 v104, v14
	v_mov_b32_e32 v105, v14
	v_mov_b32_e32 v106, v14
	v_mov_b32_e32 v107, v14
	v_mov_b32_e32 v108, v14
	v_mov_b32_e32 v109, v14
	v_mov_b32_e32 v118, v14
	v_mov_b32_e32 v119, v14
	v_mov_b32_e32 v120, v14
	v_mov_b32_e32 v121, v14
	v_mov_b32_e32 v122, v14
	v_mov_b32_e32 v123, v14
	v_mov_b32_e32 v124, v14
	v_mov_b32_e32 v125, v14
	v_mov_b32_e32 v134, v14
	v_mov_b32_e32 v135, v14
	v_mov_b32_e32 v136, v14
	v_mov_b32_e32 v137, v14
	v_mov_b32_e32 v138, v14
	v_mov_b32_e32 v139, v14
	v_mov_b32_e32 v140, v14
	v_mov_b32_e32 v141, v14
	v_mov_b32_e32 v218, v158
	v_mov_b32_e32 v219, v8
	v_mov_b32_e32 v220, v160
	v_mov_b32_e32 v221, v162
.LBB13_1074:
	ds_read_b128 v[142:145], v171
	ds_read_b128 v[146:149], v171 offset:1024
	ds_read_b128 v[150:153], v171 offset:2048
	ds_read_b128 v[154:157], v171 offset:3072
	ds_read_b128 v[164:167], v172
	ds_read_b128 v[174:177], v172 offset:1024
	ds_read_b128 v[178:181], v172 offset:2048
	ds_read_b128 v[182:185], v172 offset:3072
	s_add_u32 s34, s8, 0x100
	s_addc_u32 s35, s9, 0
	s_cmp_eq_u32 s61, 12
	s_cselect_b32 s40, s57, s34
	s_cselect_b32 s41, s19, s35
	s_cselect_b32 s38, s58, s59
	s_cselect_b32 s39, s21, s60
	s_add_u32 s36, s40, 0x80
	s_addc_u32 s37, s41, 0
	s_add_u32 s8, s8, 0x40080
	s_addc_u32 s9, s9, 0
	s_add_i32 m0, s29, 0xc000
	ds_read_b128 v[186:189], v173
	ds_read_b128 v[190:193], v173 offset:1024
	ds_read_b128 v[194:197], v173 offset:2048
	ds_read_b128 v[198:201], v173 offset:3072
	ds_read_b128 v[202:205], v173 offset:4096
	ds_read_b128 v[206:209], v173 offset:5120
	ds_read_b128 v[210:213], v173 offset:6144
	ds_read_b128 v[214:217], v173 offset:7168
	s_nop 0
	global_load_lds_dwordx4 v218, s[8:9]
	s_add_i32 m0, s29, 0xe000
	s_nop 0
	global_load_lds_dwordx4 v220, s[8:9]
	s_cmp_lg_u32 s61, -2
	s_cbranch_scc1 .Lff1a_w8_0
	s_cmp_eq_u32 s56, 0
	s_cbranch_scc1 .Lff1a_w8_0
	s_waitcnt vmcnt(24)
	s_branch .Lff1a_wd_0

; #define PG8_STAGE(bufoff, gbase, voff) do { const char* gb_ = (const char*)(gbase); asm volatile("" : "+s"(gb_));     \
;         _Pragma("unroll") for (int _i = 0; _i < 2; ++_i) \
;         __builtin_amdgcn_global_load_lds((const unsigned*)(gb_ + (voff)[_i]), (PG8_LAS unsigned*)(lds + (bufoff) + ldsw + _i * 8192), 16, 0, 0); } while (0)
; #define PG8_LDA(dst, b, h) do { _Pragma("unroll") for (int m = 0; m < 4; ++m) _Pragma("unroll") for (int k = 0; k < 2; ++k) dst[m][k] = *(const PG8_LAS bf16x8*)(lds + PG8_SA(b, h) + aoff + m * 2048 + k * 1024); } while (0)
; #define PG8_LDB(dst, b, h) do { _Pragma("unroll") for (int n = 0; n < 2; ++n) _Pragma("unroll") for (int k = 0; k < 2; ++k) dst[n][k] = *(const PG8_LAS bf16x8*)(lds + PG8_SB(b, h) + boff + n * 2048 + k * 1024); } while (0)
; #define PG8_MMA(ai, bj, At, Bt) do { __builtin_amdgcn_s_setprio(1); _Pragma("unroll") for (int m = 0; m < 4; ++m) _Pragma("unroll") for (int n = 0; n < 2; ++n) _Pragma("unroll") for (int k = 0; k < 2; ++k) \
;         acc[ai][bj][m][n] = __builtin_amdgcn_mfma_f32_16x16x32_bf16(Bt[n][k], At[m][k], acc[ai][bj][m][n], 0, 0, 0); __builtin_amdgcn_s_setprio(0); } while (0)
; #define PG8_WAIT_V(n) asm volatile("s_waitcnt vmcnt(" #n ")" ::: "memory")
; #define PG8_WAIT_L(n) asm volatile("s_waitcnt lgkmcnt(" #n ")" ::: "memory")
; #define PG8_BAR __builtin_amdgcn_s_barrier()
; #define PG8_SCHED __builtin_amdgcn_sched_barrier(0)
; template <class Epi, class Sched, bool ALIGN_EPI = false, bool SP2 = false>
; __device__ __forceinline__ void gemm_phase(PG8_LAS unsigned char* lds, const Gemm g, const Sched& S, const Epi& E, int wid0) {
;     ...
;             PG8_WAIT_V(8); PG8_WAIT_L(0); PG8_BAR; PG8_MMA(0, 0, At, B0); PG8_MMA(0, 1, At, B1); PG8_BAR; PG8_SCHED;
;             PG8_LDA(At, 0, 1); PG8_STAGE(PG8_SB(0, 0), b2, vB_); PG8_STAGE(PG8_SB(0, 1), b2 + hstep, vB_); PG8_STAGE(PG8_SA(0, 0), a2, vA_);
;             PG8_WAIT_V(8); PG8_WAIT_L(0); PG8_BAR; PG8_MMA(1, 0, At, B0); PG8_MMA(1, 1, At, B1); PG8_BAR; PG8_SCHED;
;             PG8_LDB(B0, 1, 0); PG8_LDB(B1, 1, 1); PG8_SCHED; PG8_LDA(At, 1, 0); PG8_STAGE(PG8_SA(0, 1), a2 + hstepA, vA_);
;             PG8_WAIT_V(8); PG8_WAIT_L(0); PG8_BAR; PG8_MMA(0, 0, At, B0); PG8_MMA(0, 1, At, B1); PG8_BAR; PG8_SCHED;
.Lff1a_wd_1:
	s_waitcnt lgkmcnt(0)
	s_barrier
	s_setprio 1
	s_waitcnt lgkmcnt(0)
	v_mfma_f32_16x16x32_bf16 v[74:77], v[142:145], v[186:189], v[74:77]
	v_mfma_f32_16x16x32_bf16 v[70:73], v[150:153], v[186:189], v[70:73]
	v_mfma_f32_16x16x32_bf16 v[58:61], v[142:145], v[194:197], v[58:61]
	v_mfma_f32_16x16x32_bf16 v[54:57], v[150:153], v[194:197], v[54:57]
	v_mfma_f32_16x16x32_bf16 v[42:45], v[142:145], v[202:205], v[42:45]
	v_mfma_f32_16x16x32_bf16 v[38:41], v[150:153], v[202:205], v[38:41]
	v_mfma_f32_16x16x32_bf16 v[26:29], v[142:145], v[210:213], v[26:29]
	v_mfma_f32_16x16x32_bf16 v[22:25], v[150:153], v[210:213], v[22:25]
	v_mfma_f32_16x16x32_bf16 v[74:77], v[146:149], v[190:193], v[74:77]
	v_mfma_f32_16x16x32_bf16 v[70:73], v[154:157], v[190:193], v[70:73]
	v_mfma_f32_16x16x32_bf16 v[58:61], v[146:149], v[198:201], v[58:61]
	v_mfma_f32_16x16x32_bf16 v[54:57], v[154:157], v[198:201], v[54:57]
	v_mfma_f32_16x16x32_bf16 v[42:45], v[146:149], v[206:209], v[42:45]
	v_mfma_f32_16x16x32_bf16 v[38:41], v[154:157], v[206:209], v[38:41]
	v_mfma_f32_16x16x32_bf16 v[26:29], v[146:149], v[214:217], v[26:29]
	v_mfma_f32_16x16x32_bf16 v[22:25], v[154:157], v[214:217], v[22:25]
	s_setprio 0
	s_setprio 1
	v_mfma_f32_16x16x32_bf16 v[66:69], v[164:167], v[186:189], v[66:69]
	v_mfma_f32_16x16x32_bf16 v[62:65], v[178:181], v[186:189], v[62:65]
	v_mfma_f32_16x16x32_bf16 v[50:53], v[164:167], v[194:197], v[50:53]
	v_mfma_f32_16x16x32_bf16 v[46:49], v[178:181], v[194:197], v[46:49]
	v_mfma_f32_16x16x32_bf16 v[34:37], v[164:167], v[202:205], v[34:37]
	v_mfma_f32_16x16x32_bf16 v[30:33], v[178:181], v[202:205], v[30:33]
	v_mfma_f32_16x16x32_bf16 v[18:21], v[164:167], v[210:213], v[18:21]
	v_mfma_f32_16x16x32_bf16 v[14:17], v[178:181], v[210:213], v[14:17]
	v_mfma_f32_16x16x32_bf16 v[66:69], v[174:177], v[190:193], v[66:69]
	v_mfma_f32_16x16x32_bf16 v[62:65], v[182:185], v[190:193], v[62:65]
	v_mfma_f32_16x16x32_bf16 v[50:53], v[174:177], v[198:201], v[50:53]
	v_mfma_f32_16x16x32_bf16 v[46:49], v[182:185], v[198:201], v[46:49]
	v_mfma_f32_16x16x32_bf16 v[34:37], v[174:177], v[206:209], v[34:37]
	v_mfma_f32_16x16x32_bf16 v[30:33], v[182:185], v[206:209], v[30:33]
	v_mfma_f32_16x16x32_bf16 v[18:21], v[174:177], v[214:217], v[18:21]
	v_mfma_f32_16x16x32_bf16 v[14:17], v[182:185], v[214:217], v[14:17]
	s_setprio 0
	s_barrier
	s_add_i32 s62, 0, 0x18000
	s_add_i32 s63, 0, 0x1c000
	v_add_u32_e32 v154, s62, v9
	v_add_u32_e32 v182, s63, v9
	ds_read_b128 v[142:145], v154
	ds_read_b128 v[146:149], v154 offset:1024
	ds_read_b128 v[150:153], v154 offset:2048
	ds_read_b128 v[154:157], v154 offset:3072
	ds_read_b128 v[164:167], v182
	ds_read_b128 v[174:177], v182 offset:1024
	ds_read_b128 v[178:181], v182 offset:2048
	ds_read_b128 v[182:185], v182 offset:3072
	s_add_u32 s8, s40, 0x40000
	s_addc_u32 s9, s41, 0
	s_mov_b32 m0, s46
	ds_read_b128 v[186:189], v173 offset:32768
	ds_read_b128 v[190:193], v173 offset:33792
	ds_read_b128 v[194:197], v173 offset:34816
	ds_read_b128 v[198:201], v173 offset:35840
	ds_read_b128 v[202:205], v173 offset:36864
	ds_read_b128 v[206:209], v173 offset:37888
	ds_read_b128 v[210:213], v173 offset:38912
	ds_read_b128 v[214:217], v173 offset:39936
	s_nop 0
	global_load_lds_dwordx4 v218, s[8:9]
	s_mov_b32 m0, s47
	s_nop 0
	global_load_lds_dwordx4 v220, s[8:9]
	s_waitcnt vmcnt(8)
	s_waitcnt lgkmcnt(0)
	s_barrier
	s_setprio 1
	s_waitcnt lgkmcnt(0)
	v_mfma_f32_16x16x32_bf16 v[138:141], v[142:145], v[186:189], v[138:141]
	v_mfma_f32_16x16x32_bf16 v[134:137], v[150:153], v[186:189], v[134:137]
	v_mfma_f32_16x16x32_bf16 v[122:125], v[142:145], v[194:197], v[122:125]
	v_mfma_f32_16x16x32_bf16 v[118:121], v[150:153], v[194:197], v[118:121]
	v_mfma_f32_16x16x32_bf16 v[106:109], v[142:145], v[202:205], v[106:109]
	v_mfma_f32_16x16x32_bf16 v[102:105], v[150:153], v[202:205], v[102:105]
	v_mfma_f32_16x16x32_bf16 v[90:93], v[142:145], v[210:213], v[90:93]
	v_mfma_f32_16x16x32_bf16 v[86:89], v[150:153], v[210:213], v[86:89]
	v_mfma_f32_16x16x32_bf16 v[138:141], v[146:149], v[190:193], v[138:141]
	v_mfma_f32_16x16x32_bf16 v[134:137], v[154:157], v[190:193], v[134:137]
	v_mfma_f32_16x16x32_bf16 v[122:125], v[146:149], v[198:201], v[122:125]
	v_mfma_f32_16x16x32_bf16 v[118:121], v[154:157], v[198:201], v[118:121]
	v_mfma_f32_16x16x32_bf16 v[106:109], v[146:149], v[206:209], v[106:109]
	v_mfma_f32_16x16x32_bf16 v[102:105], v[154:157], v[206:209], v[102:105]
	v_mfma_f32_16x16x32_bf16 v[90:93], v[146:149], v[214:217], v[90:93]
	v_mfma_f32_16x16x32_bf16 v[86:89], v[154:157], v[214:217], v[86:89]
	s_setprio 0
	s_setprio 1
	v_mfma_f32_16x16x32_bf16 v[130:133], v[164:167], v[186:189], v[130:133]
	v_mfma_f32_16x16x32_bf16 v[126:129], v[178:181], v[186:189], v[126:129]
	v_mfma_f32_16x16x32_bf16 v[114:117], v[164:167], v[194:197], v[114:117]
	v_mfma_f32_16x16x32_bf16 v[110:113], v[178:181], v[194:197], v[110:113]
	v_mfma_f32_16x16x32_bf16 v[98:101], v[164:167], v[202:205], v[98:101]
	v_mfma_f32_16x16x32_bf16 v[94:97], v[178:181], v[202:205], v[94:97]
	v_mfma_f32_16x16x32_bf16 v[82:85], v[164:167], v[210:213], v[82:85]
	v_mfma_f32_16x16x32_bf16 v[78:81], v[178:181], v[210:213], v[78:81]
	v_mfma_f32_16x16x32_bf16 v[130:133], v[174:177], v[190:193], v[130:133]
	v_mfma_f32_16x16x32_bf16 v[126:129], v[182:185], v[190:193], v[126:129]
	v_mfma_f32_16x16x32_bf16 v[114:117], v[174:177], v[198:201], v[114:117]
	v_mfma_f32_16x16x32_bf16 v[110:113], v[182:185], v[198:201], v[110:113]
	v_mfma_f32_16x16x32_bf16 v[98:101], v[174:177], v[206:209], v[98:101]
	v_mfma_f32_16x16x32_bf16 v[94:97], v[182:185], v[206:209], v[94:97]
	v_mfma_f32_16x16x32_bf16 v[82:85], v[174:177], v[214:217], v[82:85]
	v_mfma_f32_16x16x32_bf16 v[78:81], v[182:185], v[214:217], v[78:81]
	s_setprio 0
	s_barrier
; #define PG8_STAGE(bufoff, gbase, voff) do { const char* gb_ = (const char*)(gbase); asm volatile("" : "+s"(gb_));     \
;         _Pragma("unroll") for (int _i = 0; _i < 2; ++_i) \
;         __builtin_amdgcn_global_load_lds((const unsigned*)(gb_ + (voff)[_i]), (PG8_LAS unsigned*)(lds + (bufoff) + ldsw + _i * 8192), 16, 0, 0); } while (0)
; #define PG8_LDA(dst, b, h) do { _Pragma("unroll") for (int m = 0; m < 4; ++m) _Pragma("unroll") for (int k = 0; k < 2; ++k) dst[m][k] = *(const PG8_LAS bf16x8*)(lds + PG8_SA(b, h) + aoff + m * 2048 + k * 1024); } while (0)
; #define PG8_MMA(ai, bj, At, Bt) do { __builtin_amdgcn_s_setprio(1); _Pragma("unroll") for (int m = 0; m < 4; ++m) _Pragma("unroll") for (int n = 0; n < 2; ++n) _Pragma("unroll") for (int k = 0; k < 2; ++k) \
;         acc[ai][bj][m][n] = __builtin_amdgcn_mfma_f32_16x16x32_bf16(Bt[n][k], At[m][k], acc[ai][bj][m][n], 0, 0, 0); __builtin_amdgcn_s_setprio(0); } while (0)
; #define PG8_WAIT_V(n) asm volatile("s_waitcnt vmcnt(" #n ")" ::: "memory")
; #define PG8_WAIT_L(n) asm volatile("s_waitcnt lgkmcnt(" #n ")" ::: "memory")
; #define PG8_BAR __builtin_amdgcn_s_barrier()
; #define PG8_SCHED __builtin_amdgcn_sched_barrier(0)
; template <class Epi, class Sched, bool ALIGN_EPI = false, bool SP2 = false>
; __device__ __forceinline__ void gemm_phase(PG8_LAS unsigned char* lds, const Gemm g, const Sched& S, const Epi& E, int wid0) {
;     ...
;             PG8_LDA(At, 1, 1); PG8_STAGE(PG8_SB(1, 0), b3, vB_); PG8_STAGE(PG8_SB(1, 1), b3 + hstep, vB_); PG8_STAGE(PG8_SA(1, 0), a3, vA_);
;             PG8_WAIT_V(8); PG8_WAIT_L(0); PG8_BAR; PG8_MMA(1, 0, At, B0); PG8_MMA(1, 1, At, B1); PG8_BAR; PG8_SCHED;
	s_add_u32 s8, s38, 0x80
	s_addc_u32 s9, s39, 0
	s_add_i32 s40, s62, s27
	s_mov_b32 m0, s40
	ds_read_b128 v[186:189], v173 offset:49152
	ds_read_b128 v[190:193], v173 offset:50176
	ds_read_b128 v[194:197], v173 offset:51200
	ds_read_b128 v[198:201], v173 offset:52224
	ds_read_b128 v[202:205], v173 offset:53248
	ds_read_b128 v[206:209], v173 offset:54272
	ds_read_b128 v[210:213], v173 offset:55296
	ds_read_b128 v[214:217], v173 offset:56320
	s_nop 0
	global_load_lds_dwordx4 v219, s[8:9]
	s_add_i32 m0, s40, 0x2000
	s_nop 0
	global_load_lds_dwordx4 v221, s[8:9]
	s_add_u32 s8, s38, 0x10080
	s_addc_u32 s9, s39, 0
	s_add_i32 s38, s63, s27
	s_mov_b32 m0, s38
	s_nop 0
	global_load_lds_dwordx4 v219, s[8:9]
	s_add_i32 m0, s38, 0x2000
	s_nop 0
	global_load_lds_dwordx4 v221, s[8:9]
	s_mov_b32 m0, s50
	s_nop 0
	global_load_lds_dwordx4 v218, s[36:37]
	s_mov_b32 m0, s51
	s_nop 0
	global_load_lds_dwordx4 v220, s[36:37]
	s_waitcnt vmcnt(8)
	s_waitcnt lgkmcnt(0)
	s_barrier
	s_setprio 1
	s_waitcnt lgkmcnt(0)
	v_mfma_f32_16x16x32_bf16 v[74:77], v[142:145], v[186:189], v[74:77]
	v_mfma_f32_16x16x32_bf16 v[70:73], v[150:153], v[186:189], v[70:73]
	v_mfma_f32_16x16x32_bf16 v[58:61], v[142:145], v[194:197], v[58:61]
	v_mfma_f32_16x16x32_bf16 v[54:57], v[150:153], v[194:197], v[54:57]
	v_mfma_f32_16x16x32_bf16 v[42:45], v[142:145], v[202:205], v[42:45]
	v_mfma_f32_16x16x32_bf16 v[38:41], v[150:153], v[202:205], v[38:41]
	v_mfma_f32_16x16x32_bf16 v[26:29], v[142:145], v[210:213], v[26:29]
	v_mfma_f32_16x16x32_bf16 v[22:25], v[150:153], v[210:213], v[22:25]
	v_mfma_f32_16x16x32_bf16 v[74:77], v[146:149], v[190:193], v[74:77]
	v_mfma_f32_16x16x32_bf16 v[70:73], v[154:157], v[190:193], v[70:73]
	v_mfma_f32_16x16x32_bf16 v[58:61], v[146:149], v[198:201], v[58:61]
	v_mfma_f32_16x16x32_bf16 v[54:57], v[154:157], v[198:201], v[54:57]
	v_mfma_f32_16x16x32_bf16 v[42:45], v[146:149], v[206:209], v[42:45]
	v_mfma_f32_16x16x32_bf16 v[38:41], v[154:157], v[206:209], v[38:41]
	v_mfma_f32_16x16x32_bf16 v[26:29], v[146:149], v[214:217], v[26:29]
	v_mfma_f32_16x16x32_bf16 v[22:25], v[154:157], v[214:217], v[22:25]
	s_setprio 0
	s_setprio 1
	v_mfma_f32_16x16x32_bf16 v[66:69], v[164:167], v[186:189], v[66:69]
	v_mfma_f32_16x16x32_bf16 v[62:65], v[178:181], v[186:189], v[62:65]
	v_mfma_f32_16x16x32_bf16 v[50:53], v[164:167], v[194:197], v[50:53]
	v_mfma_f32_16x16x32_bf16 v[46:49], v[178:181], v[194:197], v[46:49]
	v_mfma_f32_16x16x32_bf16 v[34:37], v[164:167], v[202:205], v[34:37]
	v_mfma_f32_16x16x32_bf16 v[30:33], v[178:181], v[202:205], v[30:33]
	v_mfma_f32_16x16x32_bf16 v[18:21], v[164:167], v[210:213], v[18:21]
	v_mfma_f32_16x16x32_bf16 v[14:17], v[178:181], v[210:213], v[14:17]
	v_mfma_f32_16x16x32_bf16 v[66:69], v[174:177], v[190:193], v[66:69]
	v_mfma_f32_16x16x32_bf16 v[62:65], v[182:185], v[190:193], v[62:65]
	v_mfma_f32_16x16x32_bf16 v[50:53], v[174:177], v[198:201], v[50:53]
	v_mfma_f32_16x16x32_bf16 v[46:49], v[182:185], v[198:201], v[46:49]
	s_add_i32 s61, s61, 2
	s_add_u32 s59, s59, 0x100
	s_addc_u32 s60, s60, 0
	s_cmp_gt_u32 s61, 13
	s_mov_b64 s[8:9], s[34:35]
	v_mov_b32_e32 v218, v158
	v_mov_b32_e32 v219, v8
	v_mov_b32_e32 v220, v160
	v_mov_b32_e32 v221, v162
	v_mfma_f32_16x16x32_bf16 v[34:37], v[174:177], v[206:209], v[34:37]
	v_mfma_f32_16x16x32_bf16 v[30:33], v[182:185], v[206:209], v[30:33]
	v_mfma_f32_16x16x32_bf16 v[18:21], v[174:177], v[214:217], v[18:21]
	v_mfma_f32_16x16x32_bf16 v[14:17], v[182:185], v[214:217], v[14:17]
	s_setprio 0
	s_barrier
	s_cbranch_scc0 .LBB13_1074
	s_and_b64 vcc, exec, s[16:17]
	s_cbranch_vccz .LBB13_1077
	s_barrier

;     __device__ float mid(int row) const { return rg(row) / ra(row); }
;     __device__ __forceinline__ bool next(int i, Unit& u) const { return map(rank + i * nloc, u); }
;     __device__ __forceinline__ bool next(int i, Unit& u) const { if (i >= __builtin_amdgcn_readfirstlane(tab[0])) return false; u.pm = __builtin_amdgcn_readfirstlane(tab[1 + 2 * i]); u.pn = __builtin_amdgcn_readfirstlane(tab[2 + 2 * i]); return true; }
; #define PG8_STAGE(bufoff, gbase, voff) do { const char* gb_ = (const char*)(gbase); asm volatile("" : "+s"(gb_));     \
;         _Pragma("unroll") for (int _i = 0; _i < 2; ++_i) \
;         __builtin_amdgcn_global_load_lds((const unsigned*)(gb_ + (voff)[_i]), (PG8_LAS unsigned*)(lds + (bufoff) + ldsw + _i * 8192), 16, 0, 0); } while (0)
; #define PG8_LDA(dst, b, h) do { _Pragma("unroll") for (int m = 0; m < 4; ++m) _Pragma("unroll") for (int k = 0; k < 2; ++k) dst[m][k] = *(const PG8_LAS bf16x8*)(lds + PG8_SA(b, h) + aoff + m * 2048 + k * 1024); } while (0)
; template <class Epi, class Sched, bool ALIGN_EPI = false, bool SP2 = false>
; __device__ __forceinline__ void gemm_phase(PG8_LAS unsigned char* lds, const Gemm g, const Sched& S, const Epi& E, int wid0) {
;     ...
;         const bool has_next = S.next(ui + 1, nxt); nxt.ui = ui + 1;
;         if constexpr (Epi::HAS_PRE) E.pre_finish(lds, cur, tid, pq0, pq1, pq2);
;         const char* nA = has_next ? (const char*)g.A + (size_t)nxt.pm * tstepA : cA; const char* nB = has_next ? (const char*)g.Bt + (size_t)nxt.pn * tstep : cB;
; #pragma nounroll
;         for (int t = 0; t < nt; t += 2) {
;             const bool last = (t == nt - 2);
;             const char* a1 = cA + (size_t)(t + 1) * kstep;
;             const char* a2 = last ? nA : cA + (size_t)(t + 2) * kstep; const char* b2 = last ? nB : cB + (size_t)(t + 2) * kstep;
;             const char* a3 = a2 + kstep; const char* b3 = b2 + kstep;
;             if (last && has_next) S.a_ready(nxt);
;             if constexpr (Epi::HAS_MID) { if (t == Epi::MID_T) E.mid(acc, cur, wr, fr); }
;             unsigned vA_[2] = {voffA[0], voffA[1]}, vB_[2] = {voffB[0], voffB[1]};
;             asm volatile("" : "+v"(vA_[0]), "+v"(vA_[1]), "+v"(vB_[0]), "+v"(vB_[1]));
;             if constexpr (SP2) {
;             PG8_LDB(B0, 0, 0); PG8_LDB(B1, 0, 1); PG8_SCHED; PG8_LDA(At, 0, 0); PG8_STAGE(PG8_SA(1, 1), a1 + hstepA, vA_);
.LBB13_1186:
	s_ashr_i32 s17, s16, 31
	s_lshl_b64 s[20:21], s[16:17], 21
	s_add_u32 s20, s42, s20
	s_addc_u32 s21, s43, s21
	s_and_b64 s[24:25], s[22:23], exec
	s_cselect_b32 s17, s21, s31
	s_cselect_b32 s27, s20, s30
	s_ashr_i32 s19, s18, 31
	s_lshl_b64 s[24:25], s[18:19], 21
	s_add_u32 s24, s44, s24
	s_addc_u32 s25, s45, s25
	s_and_b64 s[36:37], s[22:23], exec
	s_cselect_b32 s19, s25, s35
	s_cselect_b32 s57, s24, s34
	s_add_u32 s58, s34, 0x100
	v_mov_b32_e32 v0, 0
	s_addc_u32 s59, s35, 0
	s_mov_b32 s60, -2
	v_mov_b32_e32 v1, v0
	v_mov_b32_e32 v2, v0
	v_mov_b32_e32 v3, v0
	v_mov_b32_e32 v4, v0
	v_mov_b32_e32 v5, v0
	v_mov_b32_e32 v6, v0
	v_mov_b32_e32 v7, v0
	v_mov_b32_e32 v8, v0
	v_mov_b32_e32 v9, v0
	v_mov_b32_e32 v10, v0
	v_mov_b32_e32 v11, v0
	v_mov_b32_e32 v12, v0
	v_mov_b32_e32 v13, v0
	v_mov_b32_e32 v14, v0
	v_mov_b32_e32 v15, v0
	v_mov_b32_e32 v16, v0
	v_mov_b32_e32 v17, v0
	v_mov_b32_e32 v18, v0
	v_mov_b32_e32 v19, v0
	v_mov_b32_e32 v20, v0
	v_mov_b32_e32 v21, v0
	v_mov_b32_e32 v22, v0
	v_mov_b32_e32 v23, v0
	v_mov_b32_e32 v24, v0
	v_mov_b32_e32 v25, v0
	v_mov_b32_e32 v26, v0
	v_mov_b32_e32 v27, v0
	v_mov_b32_e32 v28, v0
	v_mov_b32_e32 v29, v0
	v_mov_b32_e32 v30, v0
	v_mov_b32_e32 v31, v0
	v_mov_b32_e32 v64, v0
	v_mov_b32_e32 v65, v0
	v_mov_b32_e32 v66, v0
	v_mov_b32_e32 v67, v0
	v_mov_b32_e32 v68, v0
	v_mov_b32_e32 v69, v0
	v_mov_b32_e32 v70, v0
	v_mov_b32_e32 v71, v0
	v_mov_b32_e32 v72, v0
	v_mov_b32_e32 v73, v0
	v_mov_b32_e32 v74, v0
	v_mov_b32_e32 v75, v0
	v_mov_b32_e32 v76, v0
	v_mov_b32_e32 v77, v0
	v_mov_b32_e32 v78, v0
	v_mov_b32_e32 v79, v0
	v_mov_b32_e32 v80, v0
	v_mov_b32_e32 v81, v0
	v_mov_b32_e32 v82, v0
	v_mov_b32_e32 v83, v0
	v_mov_b32_e32 v84, v0
	v_mov_b32_e32 v85, v0
	v_mov_b32_e32 v86, v0
	v_mov_b32_e32 v87, v0
	v_mov_b32_e32 v88, v0
	v_mov_b32_e32 v89, v0
	v_mov_b32_e32 v90, v0
	v_mov_b32_e32 v91, v0
	v_mov_b32_e32 v92, v0
	v_mov_b32_e32 v93, v0
	v_mov_b32_e32 v94, v0
	v_mov_b32_e32 v95, v0
	v_mov_b32_e32 v32, v0
	v_mov_b32_e32 v33, v0
	v_mov_b32_e32 v34, v0
	v_mov_b32_e32 v35, v0
	v_mov_b32_e32 v36, v0
	v_mov_b32_e32 v37, v0
	v_mov_b32_e32 v38, v0
	v_mov_b32_e32 v39, v0
	v_mov_b32_e32 v40, v0
	v_mov_b32_e32 v41, v0
	v_mov_b32_e32 v42, v0
	v_mov_b32_e32 v43, v0
	v_mov_b32_e32 v44, v0
	v_mov_b32_e32 v45, v0
	v_mov_b32_e32 v46, v0
	v_mov_b32_e32 v47, v0
	v_mov_b32_e32 v48, v0
	v_mov_b32_e32 v49, v0
	v_mov_b32_e32 v50, v0
	v_mov_b32_e32 v51, v0
	v_mov_b32_e32 v52, v0
	v_mov_b32_e32 v53, v0
	v_mov_b32_e32 v54, v0
	v_mov_b32_e32 v55, v0
	v_mov_b32_e32 v56, v0
	v_mov_b32_e32 v57, v0
	v_mov_b32_e32 v58, v0
	v_mov_b32_e32 v59, v0
	v_mov_b32_e32 v60, v0
	v_mov_b32_e32 v61, v0
	v_mov_b32_e32 v62, v0
	v_mov_b32_e32 v63, v0
	v_mov_b32_e32 v96, v0
	v_mov_b32_e32 v97, v0
	v_mov_b32_e32 v98, v0
	v_mov_b32_e32 v99, v0
	v_mov_b32_e32 v100, v0
	v_mov_b32_e32 v101, v0
	v_mov_b32_e32 v102, v0
	v_mov_b32_e32 v103, v0
	v_mov_b32_e32 v104, v0
	v_mov_b32_e32 v105, v0
	v_mov_b32_e32 v106, v0
	v_mov_b32_e32 v107, v0
	v_mov_b32_e32 v108, v0
	v_mov_b32_e32 v109, v0
	v_mov_b32_e32 v110, v0
	v_mov_b32_e32 v111, v0
	v_mov_b32_e32 v112, v0
	v_mov_b32_e32 v113, v0
	v_mov_b32_e32 v114, v0
	v_mov_b32_e32 v115, v0
	v_mov_b32_e32 v116, v0
	v_mov_b32_e32 v117, v0
	v_mov_b32_e32 v118, v0
	v_mov_b32_e32 v119, v0
	v_mov_b32_e32 v120, v0
	v_mov_b32_e32 v121, v0
	v_mov_b32_e32 v122, v0
	v_mov_b32_e32 v123, v0
	v_mov_b32_e32 v124, v0
	v_mov_b32_e32 v125, v0
	v_mov_b32_e32 v126, v0
	v_mov_b32_e32 v127, v0
	v_mov_b32_e32 v181, v162
	v_mov_b32_e32 v202, v156
	v_mov_b32_e32 v203, v158
	v_mov_b32_e32 v204, v160
.LBB13_1187:
	ds_read_b128 v[128:131], v161
	ds_read_b128 v[132:135], v161 offset:1024
	ds_read_b128 v[136:139], v161 offset:2048
	ds_read_b128 v[140:143], v161 offset:3072
	ds_read_b128 v[144:147], v163
	ds_read_b128 v[148:151], v163 offset:1024
	ds_read_b128 v[152:155], v163 offset:2048
	ds_read_b128 v[164:167], v163 offset:3072
	s_add_u32 s34, s30, 0x100
	s_addc_u32 s35, s31, 0
	s_cmp_eq_u32 s60, 60
	s_cselect_b32 s40, s27, s34
	s_cselect_b32 s41, s17, s35
	s_cselect_b32 s38, s57, s58
	s_cselect_b32 s39, s19, s59
	s_add_u32 s36, s40, 0x80
	s_addc_u32 s37, s41, 0
	s_add_u32 s30, s30, 0x100080
	s_addc_u32 s31, s31, 0
	s_add_i32 m0, s29, 0xc000
	ds_read_b128 v[168:171], v180
	ds_read_b128 v[172:175], v180 offset:1024
	ds_read_b128 v[176:179], v180 offset:2048
	ds_read_b128 v[182:185], v180 offset:3072
	ds_read_b128 v[186:189], v180 offset:4096
	ds_read_b128 v[190:193], v180 offset:5120
	ds_read_b128 v[194:197], v180 offset:6144
	ds_read_b128 v[198:201], v180 offset:7168
	s_nop 0
	global_load_lds_dwordx4 v202, s[30:31]
	s_add_i32 m0, s29, 0xe000
	s_nop 0
	global_load_lds_dwordx4 v204, s[30:31]
	s_waitcnt vmcnt(8)
	s_waitcnt lgkmcnt(0)
	s_barrier
; #define PG8_STAGE(bufoff, gbase, voff) do { const char* gb_ = (const char*)(gbase); asm volatile("" : "+s"(gb_));     \
;         _Pragma("unroll") for (int _i = 0; _i < 2; ++_i) \
;         __builtin_amdgcn_global_load_lds((const unsigned*)(gb_ + (voff)[_i]), (PG8_LAS unsigned*)(lds + (bufoff) + ldsw + _i * 8192), 16, 0, 0); } while (0)
; #define PG8_LDA(dst, b, h) do { _Pragma("unroll") for (int m = 0; m < 4; ++m) _Pragma("unroll") for (int k = 0; k < 2; ++k) dst[m][k] = *(const PG8_LAS bf16x8*)(lds + PG8_SA(b, h) + aoff + m * 2048 + k * 1024); } while (0)
; #define PG8_LDB(dst, b, h) do { _Pragma("unroll") for (int n = 0; n < 2; ++n) _Pragma("unroll") for (int k = 0; k < 2; ++k) dst[n][k] = *(const PG8_LAS bf16x8*)(lds + PG8_SB(b, h) + boff + n * 2048 + k * 1024); } while (0)
; #define PG8_MMA(ai, bj, At, Bt) do { __builtin_amdgcn_s_setprio(1); _Pragma("unroll") for (int m = 0; m < 4; ++m) _Pragma("unroll") for (int n = 0; n < 2; ++n) _Pragma("unroll") for (int k = 0; k < 2; ++k) \
;         acc[ai][bj][m][n] = __builtin_amdgcn_mfma_f32_16x16x32_bf16(Bt[n][k], At[m][k], acc[ai][bj][m][n], 0, 0, 0); __builtin_amdgcn_s_setprio(0); } while (0)
; #define PG8_WAIT_V(n) asm volatile("s_waitcnt vmcnt(" #n ")" ::: "memory")
; #define PG8_WAIT_L(n) asm volatile("s_waitcnt lgkmcnt(" #n ")" ::: "memory")
; #define PG8_BAR __builtin_amdgcn_s_barrier()
; #define PG8_SCHED __builtin_amdgcn_sched_barrier(0)
; template <class Epi, class Sched, bool ALIGN_EPI = false, bool SP2 = false>
; __device__ __forceinline__ void gemm_phase(PG8_LAS unsigned char* lds, const Gemm g, const Sched& S, const Epi& E, int wid0) {
;     ...
;             PG8_LDB(B0, 0, 0); PG8_LDB(B1, 0, 1); PG8_SCHED; PG8_LDA(At, 0, 0); PG8_STAGE(PG8_SA(1, 1), a1 + hstepA, vA_);
;             PG8_WAIT_V(8); PG8_WAIT_L(0); PG8_BAR; PG8_MMA(0, 0, At, B0); PG8_MMA(0, 1, At, B1); PG8_BAR; PG8_SCHED;
;             PG8_LDA(At, 0, 1); PG8_STAGE(PG8_SB(0, 0), b2, vB_); PG8_STAGE(PG8_SB(0, 1), b2 + hstep, vB_); PG8_STAGE(PG8_SA(0, 0), a2, vA_);
;             PG8_WAIT_V(8); PG8_WAIT_L(0); PG8_BAR; PG8_MMA(1, 0, At, B0); PG8_MMA(1, 1, At, B1); PG8_BAR; PG8_SCHED;
	s_setprio 1
	s_waitcnt lgkmcnt(0)
	v_mfma_f32_16x16x32_bf16 v[124:127], v[128:131], v[168:171], v[124:127]
	v_mfma_f32_16x16x32_bf16 v[120:123], v[136:139], v[168:171], v[120:123]
	v_mfma_f32_16x16x32_bf16 v[116:119], v[128:131], v[176:179], v[116:119]
	v_mfma_f32_16x16x32_bf16 v[112:115], v[136:139], v[176:179], v[112:115]
	v_mfma_f32_16x16x32_bf16 v[108:111], v[128:131], v[186:189], v[108:111]
	v_mfma_f32_16x16x32_bf16 v[104:107], v[136:139], v[186:189], v[104:107]
	v_mfma_f32_16x16x32_bf16 v[100:103], v[128:131], v[194:197], v[100:103]
	v_mfma_f32_16x16x32_bf16 v[96:99], v[136:139], v[194:197], v[96:99]
	v_mfma_f32_16x16x32_bf16 v[124:127], v[132:135], v[172:175], v[124:127]
	v_mfma_f32_16x16x32_bf16 v[120:123], v[140:143], v[172:175], v[120:123]
	v_mfma_f32_16x16x32_bf16 v[116:119], v[132:135], v[182:185], v[116:119]
	v_mfma_f32_16x16x32_bf16 v[112:115], v[140:143], v[182:185], v[112:115]
	v_mfma_f32_16x16x32_bf16 v[108:111], v[132:135], v[190:193], v[108:111]
	v_mfma_f32_16x16x32_bf16 v[104:107], v[140:143], v[190:193], v[104:107]
	v_mfma_f32_16x16x32_bf16 v[100:103], v[132:135], v[198:201], v[100:103]
	v_mfma_f32_16x16x32_bf16 v[96:99], v[140:143], v[198:201], v[96:99]
	s_setprio 0
	s_setprio 1
	v_mfma_f32_16x16x32_bf16 v[60:63], v[144:147], v[168:171], v[60:63]
	v_mfma_f32_16x16x32_bf16 v[56:59], v[152:155], v[168:171], v[56:59]
	v_mfma_f32_16x16x32_bf16 v[52:55], v[144:147], v[176:179], v[52:55]
	v_mfma_f32_16x16x32_bf16 v[48:51], v[152:155], v[176:179], v[48:51]
	v_mfma_f32_16x16x32_bf16 v[44:47], v[144:147], v[186:189], v[44:47]
	v_mfma_f32_16x16x32_bf16 v[40:43], v[152:155], v[186:189], v[40:43]
	v_mfma_f32_16x16x32_bf16 v[36:39], v[144:147], v[194:197], v[36:39]
	v_mfma_f32_16x16x32_bf16 v[32:35], v[152:155], v[194:197], v[32:35]
	v_mfma_f32_16x16x32_bf16 v[60:63], v[148:151], v[172:175], v[60:63]
	v_mfma_f32_16x16x32_bf16 v[56:59], v[164:167], v[172:175], v[56:59]
	v_mfma_f32_16x16x32_bf16 v[52:55], v[148:151], v[182:185], v[52:55]
	v_mfma_f32_16x16x32_bf16 v[48:51], v[164:167], v[182:185], v[48:51]
	v_mfma_f32_16x16x32_bf16 v[44:47], v[148:151], v[190:193], v[44:47]
	v_mfma_f32_16x16x32_bf16 v[40:43], v[164:167], v[190:193], v[40:43]
	v_mfma_f32_16x16x32_bf16 v[36:39], v[148:151], v[198:201], v[36:39]
	v_mfma_f32_16x16x32_bf16 v[32:35], v[164:167], v[198:201], v[32:35]
	s_setprio 0
	s_barrier
	s_add_i32 s61, s55, s33
	s_mov_b64 s[30:31], s[38:39]
	s_mov_b32 m0, s61
	ds_read_b128 v[168:171], v180 offset:16384
	ds_read_b128 v[172:175], v180 offset:17408
	ds_read_b128 v[176:179], v180 offset:18432
	ds_read_b128 v[182:185], v180 offset:19456
	ds_read_b128 v[186:189], v180 offset:20480
	ds_read_b128 v[190:193], v180 offset:21504
	ds_read_b128 v[194:197], v180 offset:22528
	ds_read_b128 v[198:201], v180 offset:23552
	s_nop 0
	global_load_lds_dwordx4 v203, s[30:31]
	s_add_i32 m0, s61, 0x2000
	s_nop 0
	global_load_lds_dwordx4 v181, s[30:31]
	s_add_u32 s30, s38, 0x100000
	s_addc_u32 s31, s39, 0
	s_add_i32 s61, s56, s33
	s_mov_b32 m0, s61
	s_nop 0
	global_load_lds_dwordx4 v203, s[30:31]
	s_add_i32 m0, s61, 0x2000
	s_nop 0
	global_load_lds_dwordx4 v181, s[30:31]
	s_mov_b64 s[30:31], s[40:41]
	s_mov_b32 m0, s29
	s_nop 0
	global_load_lds_dwordx4 v202, s[30:31]
	s_mov_b32 m0, s46
	s_nop 0
	global_load_lds_dwordx4 v204, s[30:31]
	s_waitcnt vmcnt(8)
	s_waitcnt lgkmcnt(0)
	s_barrier
	s_setprio 1
	s_waitcnt lgkmcnt(0)
	v_mfma_f32_16x16x32_bf16 v[92:95], v[128:131], v[168:171], v[92:95]
	v_mfma_f32_16x16x32_bf16 v[88:91], v[136:139], v[168:171], v[88:91]
	v_mfma_f32_16x16x32_bf16 v[84:87], v[128:131], v[176:179], v[84:87]
	v_mfma_f32_16x16x32_bf16 v[80:83], v[136:139], v[176:179], v[80:83]
	v_mfma_f32_16x16x32_bf16 v[76:79], v[128:131], v[186:189], v[76:79]
	v_mfma_f32_16x16x32_bf16 v[72:75], v[136:139], v[186:189], v[72:75]
	v_mfma_f32_16x16x32_bf16 v[68:71], v[128:131], v[194:197], v[68:71]
	v_mfma_f32_16x16x32_bf16 v[64:67], v[136:139], v[194:197], v[64:67]
	v_mfma_f32_16x16x32_bf16 v[92:95], v[132:135], v[172:175], v[92:95]
	v_mfma_f32_16x16x32_bf16 v[88:91], v[140:143], v[172:175], v[88:91]
	v_mfma_f32_16x16x32_bf16 v[84:87], v[132:135], v[182:185], v[84:87]
	v_mfma_f32_16x16x32_bf16 v[80:83], v[140:143], v[182:185], v[80:83]
	v_mfma_f32_16x16x32_bf16 v[76:79], v[132:135], v[190:193], v[76:79]
	v_mfma_f32_16x16x32_bf16 v[72:75], v[140:143], v[190:193], v[72:75]
	v_mfma_f32_16x16x32_bf16 v[68:71], v[132:135], v[198:201], v[68:71]
	v_mfma_f32_16x16x32_bf16 v[64:67], v[140:143], v[198:201], v[64:67]
	s_setprio 0
	s_setprio 1
	v_mfma_f32_16x16x32_bf16 v[28:31], v[144:147], v[168:171], v[28:31]
	v_mfma_f32_16x16x32_bf16 v[24:27], v[152:155], v[168:171], v[24:27]
	v_mfma_f32_16x16x32_bf16 v[20:23], v[144:147], v[176:179], v[20:23]
	v_mfma_f32_16x16x32_bf16 v[16:19], v[152:155], v[176:179], v[16:19]
	v_mfma_f32_16x16x32_bf16 v[12:15], v[144:147], v[186:189], v[12:15]
	v_mfma_f32_16x16x32_bf16 v[8:11], v[152:155], v[186:189], v[8:11]
	v_mfma_f32_16x16x32_bf16 v[4:7], v[144:147], v[194:197], v[4:7]
	v_mfma_f32_16x16x32_bf16 v[0:3], v[152:155], v[194:197], v[0:3]
	v_mfma_f32_16x16x32_bf16 v[28:31], v[148:151], v[172:175], v[28:31]
	v_mfma_f32_16x16x32_bf16 v[24:27], v[164:167], v[172:175], v[24:27]
	v_mfma_f32_16x16x32_bf16 v[20:23], v[148:151], v[182:185], v[20:23]
	v_mfma_f32_16x16x32_bf16 v[16:19], v[164:167], v[182:185], v[16:19]
	v_mfma_f32_16x16x32_bf16 v[12:15], v[148:151], v[190:193], v[12:15]
	v_mfma_f32_16x16x32_bf16 v[8:11], v[164:167], v[190:193], v[8:11]
	v_mfma_f32_16x16x32_bf16 v[4:7], v[148:151], v[198:201], v[4:7]
	v_mfma_f32_16x16x32_bf16 v[0:3], v[164:167], v[198:201], v[0:3]
	s_setprio 0
	s_barrier
; #define PG8_STAGE(bufoff, gbase, voff) do { const char* gb_ = (const char*)(gbase); asm volatile("" : "+s"(gb_));     \
;         _Pragma("unroll") for (int _i = 0; _i < 2; ++_i) \
;         __builtin_amdgcn_global_load_lds((const unsigned*)(gb_ + (voff)[_i]), (PG8_LAS unsigned*)(lds + (bufoff) + ldsw + _i * 8192), 16, 0, 0); } while (0)
; #define PG8_LDA(dst, b, h) do { _Pragma("unroll") for (int m = 0; m < 4; ++m) _Pragma("unroll") for (int k = 0; k < 2; ++k) dst[m][k] = *(const PG8_LAS bf16x8*)(lds + PG8_SA(b, h) + aoff + m * 2048 + k * 1024); } while (0)
; #define PG8_LDB(dst, b, h) do { _Pragma("unroll") for (int n = 0; n < 2; ++n) _Pragma("unroll") for (int k = 0; k < 2; ++k) dst[n][k] = *(const PG8_LAS bf16x8*)(lds + PG8_SB(b, h) + boff + n * 2048 + k * 1024); } while (0)
; #define PG8_MMA(ai, bj, At, Bt) do { __builtin_amdgcn_s_setprio(1); _Pragma("unroll") for (int m = 0; m < 4; ++m) _Pragma("unroll") for (int n = 0; n < 2; ++n) _Pragma("unroll") for (int k = 0; k < 2; ++k) \
;         acc[ai][bj][m][n] = __builtin_amdgcn_mfma_f32_16x16x32_bf16(Bt[n][k], At[m][k], acc[ai][bj][m][n], 0, 0, 0); __builtin_amdgcn_s_setprio(0); } while (0)
; #define PG8_WAIT_V(n) asm volatile("s_waitcnt vmcnt(" #n ")" ::: "memory")
; #define PG8_WAIT_L(n) asm volatile("s_waitcnt lgkmcnt(" #n ")" ::: "memory")
; #define PG8_BAR __builtin_amdgcn_s_barrier()
; #define PG8_SCHED __builtin_amdgcn_sched_barrier(0)
; template <class Epi, class Sched, bool ALIGN_EPI = false, bool SP2 = false>
; __device__ __forceinline__ void gemm_phase(PG8_LAS unsigned char* lds, const Gemm g, const Sched& S, const Epi& E, int wid0) {
;     ...
;             PG8_LDB(B0, 1, 0); PG8_LDB(B1, 1, 1); PG8_SCHED; PG8_LDA(At, 1, 0); PG8_STAGE(PG8_SA(0, 1), a2 + hstepA, vA_);
;             PG8_WAIT_V(8); PG8_WAIT_L(0); PG8_BAR; PG8_MMA(0, 0, At, B0); PG8_MMA(0, 1, At, B1); PG8_BAR; PG8_SCHED;
;             PG8_LDA(At, 1, 1); PG8_STAGE(PG8_SB(1, 0), b3, vB_); PG8_STAGE(PG8_SB(1, 1), b3 + hstep, vB_); PG8_STAGE(PG8_SA(1, 0), a3, vA_);
;             PG8_WAIT_V(8); PG8_WAIT_L(0); PG8_BAR; PG8_MMA(1, 0, At, B0); PG8_MMA(1, 1, At, B1); PG8_BAR; PG8_SCHED;
	s_add_i32 s61, 0, 0x18000
	s_add_i32 s62, 0, 0x1c000
	v_add_u32_e32 v140, s61, v157
	v_add_u32_e32 v164, s62, v157
	ds_read_b128 v[128:131], v140
	ds_read_b128 v[132:135], v140 offset:1024
	ds_read_b128 v[136:139], v140 offset:2048
	ds_read_b128 v[140:143], v140 offset:3072
	ds_read_b128 v[144:147], v164
	ds_read_b128 v[148:151], v164 offset:1024
	ds_read_b128 v[152:155], v164 offset:2048
	ds_read_b128 v[164:167], v164 offset:3072
	s_add_u32 s30, s40, 0x100000
	s_addc_u32 s31, s41, 0
	s_mov_b32 m0, s47
	ds_read_b128 v[168:171], v180 offset:32768
	ds_read_b128 v[172:175], v180 offset:33792
	ds_read_b128 v[176:179], v180 offset:34816
	ds_read_b128 v[182:185], v180 offset:35840
	ds_read_b128 v[186:189], v180 offset:36864
	ds_read_b128 v[190:193], v180 offset:37888
	ds_read_b128 v[194:197], v180 offset:38912
	ds_read_b128 v[198:201], v180 offset:39936
	s_nop 0
	global_load_lds_dwordx4 v202, s[30:31]
	s_mov_b32 m0, s48
	s_nop 0
	global_load_lds_dwordx4 v204, s[30:31]
	s_waitcnt vmcnt(8)
	s_waitcnt lgkmcnt(0)
	s_barrier
	s_setprio 1
	s_waitcnt lgkmcnt(0)
	v_mfma_f32_16x16x32_bf16 v[124:127], v[128:131], v[168:171], v[124:127]
	v_mfma_f32_16x16x32_bf16 v[120:123], v[136:139], v[168:171], v[120:123]
	v_mfma_f32_16x16x32_bf16 v[116:119], v[128:131], v[176:179], v[116:119]
	v_mfma_f32_16x16x32_bf16 v[112:115], v[136:139], v[176:179], v[112:115]
	v_mfma_f32_16x16x32_bf16 v[108:111], v[128:131], v[186:189], v[108:111]
	v_mfma_f32_16x16x32_bf16 v[104:107], v[136:139], v[186:189], v[104:107]
	v_mfma_f32_16x16x32_bf16 v[100:103], v[128:131], v[194:197], v[100:103]
	v_mfma_f32_16x16x32_bf16 v[96:99], v[136:139], v[194:197], v[96:99]
	v_mfma_f32_16x16x32_bf16 v[124:127], v[132:135], v[172:175], v[124:127]
	v_mfma_f32_16x16x32_bf16 v[120:123], v[140:143], v[172:175], v[120:123]
	v_mfma_f32_16x16x32_bf16 v[116:119], v[132:135], v[182:185], v[116:119]
	v_mfma_f32_16x16x32_bf16 v[112:115], v[140:143], v[182:185], v[112:115]
	v_mfma_f32_16x16x32_bf16 v[108:111], v[132:135], v[190:193], v[108:111]
	v_mfma_f32_16x16x32_bf16 v[104:107], v[140:143], v[190:193], v[104:107]
	v_mfma_f32_16x16x32_bf16 v[100:103], v[132:135], v[198:201], v[100:103]
	v_mfma_f32_16x16x32_bf16 v[96:99], v[140:143], v[198:201], v[96:99]
	s_setprio 0
	s_setprio 1
	v_mfma_f32_16x16x32_bf16 v[60:63], v[144:147], v[168:171], v[60:63]
	v_mfma_f32_16x16x32_bf16 v[56:59], v[152:155], v[168:171], v[56:59]
	v_mfma_f32_16x16x32_bf16 v[52:55], v[144:147], v[176:179], v[52:55]
	v_mfma_f32_16x16x32_bf16 v[48:51], v[152:155], v[176:179], v[48:51]
	v_mfma_f32_16x16x32_bf16 v[44:47], v[144:147], v[186:189], v[44:47]
	v_mfma_f32_16x16x32_bf16 v[40:43], v[152:155], v[186:189], v[40:43]
	v_mfma_f32_16x16x32_bf16 v[36:39], v[144:147], v[194:197], v[36:39]
	v_mfma_f32_16x16x32_bf16 v[32:35], v[152:155], v[194:197], v[32:35]
	v_mfma_f32_16x16x32_bf16 v[60:63], v[148:151], v[172:175], v[60:63]
	v_mfma_f32_16x16x32_bf16 v[56:59], v[164:167], v[172:175], v[56:59]
	v_mfma_f32_16x16x32_bf16 v[52:55], v[148:151], v[182:185], v[52:55]
	v_mfma_f32_16x16x32_bf16 v[48:51], v[164:167], v[182:185], v[48:51]
	v_mfma_f32_16x16x32_bf16 v[44:47], v[148:151], v[190:193], v[44:47]
	v_mfma_f32_16x16x32_bf16 v[40:43], v[164:167], v[190:193], v[40:43]
	v_mfma_f32_16x16x32_bf16 v[36:39], v[148:151], v[198:201], v[36:39]
	v_mfma_f32_16x16x32_bf16 v[32:35], v[164:167], v[198:201], v[32:35]
	s_setprio 0
	s_barrier
	s_add_u32 s30, s38, 0x80
	s_addc_u32 s31, s39, 0
	s_add_i32 s40, s61, s33
	s_mov_b32 m0, s40
	ds_read_b128 v[168:171], v180 offset:49152
	ds_read_b128 v[172:175], v180 offset:50176
	ds_read_b128 v[176:179], v180 offset:51200
	ds_read_b128 v[182:185], v180 offset:52224
	ds_read_b128 v[186:189], v180 offset:53248
	ds_read_b128 v[190:193], v180 offset:54272
	ds_read_b128 v[194:197], v180 offset:55296
	ds_read_b128 v[198:201], v180 offset:56320
	s_nop 0
	global_load_lds_dwordx4 v203, s[30:31]
	s_add_i32 m0, s40, 0x2000
	s_nop 0
	global_load_lds_dwordx4 v181, s[30:31]
	s_add_u32 s30, s38, 0x100080
	s_addc_u32 s31, s39, 0
	s_add_i32 s38, s62, s33
	s_mov_b32 m0, s38
	s_nop 0
	global_load_lds_dwordx4 v203, s[30:31]
	s_add_i32 m0, s38, 0x2000
	s_nop 0
	global_load_lds_dwordx4 v181, s[30:31]
	s_mov_b32 m0, s53
	s_nop 0
	global_load_lds_dwordx4 v202, s[36:37]
	s_mov_b32 m0, s54
	s_nop 0
	global_load_lds_dwordx4 v204, s[36:37]
	s_waitcnt vmcnt(8)
	s_waitcnt lgkmcnt(0)
	s_barrier
	s_setprio 1
	s_waitcnt lgkmcnt(0)
	v_mfma_f32_16x16x32_bf16 v[92:95], v[128:131], v[168:171], v[92:95]
	v_mfma_f32_16x16x32_bf16 v[88:91], v[136:139], v[168:171], v[88:91]
	v_mfma_f32_16x16x32_bf16 v[84:87], v[128:131], v[176:179], v[84:87]
	v_mfma_f32_16x16x32_bf16 v[80:83], v[136:139], v[176:179], v[80:83]
	v_mfma_f32_16x16x32_bf16 v[76:79], v[128:131], v[186:189], v[76:79]
	v_mfma_f32_16x16x32_bf16 v[72:75], v[136:139], v[186:189], v[72:75]
	v_mfma_f32_16x16x32_bf16 v[68:71], v[128:131], v[194:197], v[68:71]
	v_mfma_f32_16x16x32_bf16 v[64:67], v[136:139], v[194:197], v[64:67]
	v_mfma_f32_16x16x32_bf16 v[92:95], v[132:135], v[172:175], v[92:95]
	v_mfma_f32_16x16x32_bf16 v[88:91], v[140:143], v[172:175], v[88:91]
	v_mfma_f32_16x16x32_bf16 v[84:87], v[132:135], v[182:185], v[84:87]
	v_mfma_f32_16x16x32_bf16 v[80:83], v[140:143], v[182:185], v[80:83]
	v_mfma_f32_16x16x32_bf16 v[76:79], v[132:135], v[190:193], v[76:79]
	v_mfma_f32_16x16x32_bf16 v[72:75], v[140:143], v[190:193], v[72:75]
	v_mfma_f32_16x16x32_bf16 v[68:71], v[132:135], v[198:201], v[68:71]
	v_mfma_f32_16x16x32_bf16 v[64:67], v[140:143], v[198:201], v[64:67]
	s_setprio 0
	s_setprio 1
	v_mfma_f32_16x16x32_bf16 v[28:31], v[144:147], v[168:171], v[28:31]
	v_mfma_f32_16x16x32_bf16 v[24:27], v[152:155], v[168:171], v[24:27]
	v_mfma_f32_16x16x32_bf16 v[20:23], v[144:147], v[176:179], v[20:23]
	v_mfma_f32_16x16x32_bf16 v[16:19], v[152:155], v[176:179], v[16:19]
	v_mfma_f32_16x16x32_bf16 v[12:15], v[144:147], v[186:189], v[12:15]
	v_mfma_f32_16x16x32_bf16 v[8:11], v[152:155], v[186:189], v[8:11]
	v_mfma_f32_16x16x32_bf16 v[4:7], v[144:147], v[194:197], v[4:7]
	v_mfma_f32_16x16x32_bf16 v[0:3], v[152:155], v[194:197], v[0:3]
	v_mfma_f32_16x16x32_bf16 v[28:31], v[148:151], v[172:175], v[28:31]
	v_mfma_f32_16x16x32_bf16 v[24:27], v[164:167], v[172:175], v[24:27]
	v_mfma_f32_16x16x32_bf16 v[20:23], v[148:151], v[182:185], v[20:23]
	v_mfma_f32_16x16x32_bf16 v[16:19], v[164:167], v[182:185], v[16:19]
	s_add_i32 s60, s60, 2
	s_add_u32 s58, s58, 0x100
	s_addc_u32 s59, s59, 0
	s_cmp_gt_u32 s60, 61
	s_mov_b64 s[30:31], s[34:35]
	v_mov_b32_e32 v181, v162
	v_mov_b32_e32 v202, v156
	v_mov_b32_e32 v203, v158
	v_mov_b32_e32 v204, v160
	v_mfma_f32_16x16x32_bf16 v[12:15], v[148:151], v[190:193], v[12:15]
	v_mfma_f32_16x16x32_bf16 v[8:11], v[164:167], v[190:193], v[8:11]
	v_mfma_f32_16x16x32_bf16 v[4:7], v[148:151], v[198:201], v[4:7]
	v_mfma_f32_16x16x32_bf16 v[0:3], v[164:167], v[198:201], v[0:3]
	s_setprio 0
	s_barrier
	s_cbranch_scc0 .LBB13_1187
	s_and_b64 vcc, exec, s[14:15]
	s_cbranch_vccz .LBB13_1190
	s_barrier

;     __device__ float mid(int row) const { return rg(row) / ra(row); }
;     __device__ __forceinline__ bool next(int i, Unit& u) const { return map(rank + i * nloc, u); }
;     __device__ __forceinline__ bool next(int i, Unit& u) const { if (i >= __builtin_amdgcn_readfirstlane(tab[0])) return false; u.pm = __builtin_amdgcn_readfirstlane(tab[1 + 2 * i]); u.pn = __builtin_amdgcn_readfirstlane(tab[2 + 2 * i]); return true; }
; #define PG8_STAGE(bufoff, gbase, voff) do { const char* gb_ = (const char*)(gbase); asm volatile("" : "+s"(gb_));     \
;         _Pragma("unroll") for (int _i = 0; _i < 2; ++_i) \
;         __builtin_amdgcn_global_load_lds((const unsigned*)(gb_ + (voff)[_i]), (PG8_LAS unsigned*)(lds + (bufoff) + ldsw + _i * 8192), 16, 0, 0); } while (0)
; #define PG8_LDA(dst, b, h) do { _Pragma("unroll") for (int m = 0; m < 4; ++m) _Pragma("unroll") for (int k = 0; k < 2; ++k) dst[m][k] = *(const PG8_LAS bf16x8*)(lds + PG8_SA(b, h) + aoff + m * 2048 + k * 1024); } while (0)
; template <class Epi, class Sched, bool ALIGN_EPI = false, bool SP2 = false>
; __device__ __forceinline__ void gemm_phase(PG8_LAS unsigned char* lds, const Gemm g, const Sched& S, const Epi& E, int wid0) {
;     ...
;         const bool has_next = S.next(ui + 1, nxt); nxt.ui = ui + 1;
;         if constexpr (Epi::HAS_PRE) E.pre_finish(lds, cur, tid, pq0, pq1, pq2);
;         const char* nA = has_next ? (const char*)g.A + (size_t)nxt.pm * tstepA : cA; const char* nB = has_next ? (const char*)g.Bt + (size_t)nxt.pn * tstep : cB;
; #pragma nounroll
;         for (int t = 0; t < nt; t += 2) {
;             const bool last = (t == nt - 2);
;             const char* a1 = cA + (size_t)(t + 1) * kstep;
;             const char* a2 = last ? nA : cA + (size_t)(t + 2) * kstep; const char* b2 = last ? nB : cB + (size_t)(t + 2) * kstep;
;             const char* a3 = a2 + kstep; const char* b3 = b2 + kstep;
;             if (last && has_next) S.a_ready(nxt);
;             if constexpr (Epi::HAS_MID) { if (t == Epi::MID_T) E.mid(acc, cur, wr, fr); }
;             unsigned vA_[2] = {voffA[0], voffA[1]}, vB_[2] = {voffB[0], voffB[1]};
;             asm volatile("" : "+v"(vA_[0]), "+v"(vA_[1]), "+v"(vB_[0]), "+v"(vB_[1]));
;             if constexpr (SP2) {
;             PG8_LDB(B0, 0, 0); PG8_LDB(B1, 0, 1); PG8_SCHED; PG8_LDA(At, 0, 0); PG8_STAGE(PG8_SA(1, 1), a1 + hstepA, vA_);
.LBB13_1333:
	s_or_b64 exec, exec, s[10:11]
	s_and_saveexec_b64 s[10:11], s[4:5]
	s_lshl_b32 s12, s33, 10
	s_and_b32 s12, s12, 0x400
	v_add_u32_e32 v8, s12, v179
	ds_write_b128 v8, v[10:13]
	s_or_b64 exec, exec, s[10:11]
	s_ashr_i32 s47, s46, 31
	s_lshl_b64 s[10:11], s[46:47], 19
	s_add_u32 s50, s60, s10
	s_addc_u32 s51, s61, s11
	s_and_b64 s[10:11], s[0:1], exec
	s_cselect_b32 s47, s51, s3
	s_cselect_b32 s78, s50, s2
	s_ashr_i32 s49, s48, 31
	s_lshl_b64 s[10:11], s[48:49], 19
	s_add_u32 s52, s62, s10
	s_addc_u32 s53, s63, s11
	s_and_b64 s[10:11], s[0:1], exec
	s_cselect_b32 s49, s53, s9
	s_cselect_b32 s79, s52, s8
	s_add_u32 s80, s8, 0x100
	s_waitcnt lgkmcnt(0)
	v_mov_b32_e32 v14, 0
	s_addc_u32 s81, s9, 0
	s_mov_b32 s82, -2
	v_mov_b32_e32 v15, v14
	v_mov_b32_e32 v16, v14
	v_mov_b32_e32 v17, v14
	v_mov_b32_e32 v18, v14
	v_mov_b32_e32 v19, v14
	v_mov_b32_e32 v20, v14
	v_mov_b32_e32 v21, v14
	v_mov_b32_e32 v30, v14
	v_mov_b32_e32 v31, v14
	v_mov_b32_e32 v32, v14
	v_mov_b32_e32 v33, v14
	v_mov_b32_e32 v34, v14
	v_mov_b32_e32 v35, v14
	v_mov_b32_e32 v36, v14
	v_mov_b32_e32 v37, v14
	v_mov_b32_e32 v46, v14
	v_mov_b32_e32 v47, v14
	v_mov_b32_e32 v48, v14
	v_mov_b32_e32 v49, v14
	v_mov_b32_e32 v50, v14
	v_mov_b32_e32 v51, v14
	v_mov_b32_e32 v52, v14
	v_mov_b32_e32 v53, v14
	v_mov_b32_e32 v62, v14
	v_mov_b32_e32 v63, v14
	v_mov_b32_e32 v64, v14
	v_mov_b32_e32 v65, v14
	v_mov_b32_e32 v66, v14
	v_mov_b32_e32 v67, v14
	v_mov_b32_e32 v68, v14
	v_mov_b32_e32 v69, v14
	v_mov_b32_e32 v22, v14
	v_mov_b32_e32 v23, v14
	v_mov_b32_e32 v24, v14
	v_mov_b32_e32 v25, v14
	v_mov_b32_e32 v26, v14
	v_mov_b32_e32 v27, v14
	v_mov_b32_e32 v28, v14
	v_mov_b32_e32 v29, v14
	v_mov_b32_e32 v38, v14
	v_mov_b32_e32 v39, v14
	v_mov_b32_e32 v40, v14
	v_mov_b32_e32 v41, v14
	v_mov_b32_e32 v42, v14
	v_mov_b32_e32 v43, v14
	v_mov_b32_e32 v44, v14
	v_mov_b32_e32 v45, v14
	v_mov_b32_e32 v54, v14
	v_mov_b32_e32 v55, v14
	v_mov_b32_e32 v56, v14
	v_mov_b32_e32 v57, v14
	v_mov_b32_e32 v58, v14
	v_mov_b32_e32 v59, v14
	v_mov_b32_e32 v60, v14
	v_mov_b32_e32 v61, v14
	v_mov_b32_e32 v70, v14
	v_mov_b32_e32 v71, v14
	v_mov_b32_e32 v72, v14
	v_mov_b32_e32 v73, v14
	v_mov_b32_e32 v74, v14
	v_mov_b32_e32 v75, v14
	v_mov_b32_e32 v76, v14
	v_mov_b32_e32 v77, v14
	v_mov_b32_e32 v78, v14
	v_mov_b32_e32 v79, v14
	v_mov_b32_e32 v80, v14
	v_mov_b32_e32 v81, v14
	v_mov_b32_e32 v86, v14
	v_mov_b32_e32 v87, v14
	v_mov_b32_e32 v88, v14
	v_mov_b32_e32 v89, v14
	v_mov_b32_e32 v110, v14
	v_mov_b32_e32 v111, v14
	v_mov_b32_e32 v112, v14
	v_mov_b32_e32 v113, v14
	v_mov_b32_e32 v114, v14
	v_mov_b32_e32 v115, v14
	v_mov_b32_e32 v116, v14
	v_mov_b32_e32 v117, v14
	v_mov_b32_e32 v126, v14
	v_mov_b32_e32 v127, v14
	v_mov_b32_e32 v128, v14
	v_mov_b32_e32 v129, v14
	v_mov_b32_e32 v130, v14
	v_mov_b32_e32 v131, v14
	v_mov_b32_e32 v132, v14
	v_mov_b32_e32 v133, v14
	v_mov_b32_e32 v142, v14
	v_mov_b32_e32 v143, v14
	v_mov_b32_e32 v144, v14
	v_mov_b32_e32 v145, v14
	v_mov_b32_e32 v146, v14
	v_mov_b32_e32 v147, v14
	v_mov_b32_e32 v148, v14
	v_mov_b32_e32 v149, v14
	v_mov_b32_e32 v98, v14
	v_mov_b32_e32 v99, v14
	v_mov_b32_e32 v100, v14
	v_mov_b32_e32 v101, v14
	v_mov_b32_e32 v106, v14
	v_mov_b32_e32 v107, v14
	v_mov_b32_e32 v108, v14
	v_mov_b32_e32 v109, v14
	v_mov_b32_e32 v118, v14
	v_mov_b32_e32 v119, v14
	v_mov_b32_e32 v120, v14
	v_mov_b32_e32 v121, v14
	v_mov_b32_e32 v122, v14
	v_mov_b32_e32 v123, v14
	v_mov_b32_e32 v124, v14
	v_mov_b32_e32 v125, v14
	v_mov_b32_e32 v134, v14
	v_mov_b32_e32 v135, v14
	v_mov_b32_e32 v136, v14
	v_mov_b32_e32 v137, v14
	v_mov_b32_e32 v138, v14
	v_mov_b32_e32 v139, v14
	v_mov_b32_e32 v140, v14
	v_mov_b32_e32 v141, v14
	v_mov_b32_e32 v150, v14
	v_mov_b32_e32 v151, v14
	v_mov_b32_e32 v152, v14
	v_mov_b32_e32 v153, v14
	v_mov_b32_e32 v154, v14
	v_mov_b32_e32 v155, v14
	v_mov_b32_e32 v156, v14
	v_mov_b32_e32 v157, v14
	v_mov_b32_e32 v8, v178
	v_mov_b32_e32 v220, v174
	v_mov_b32_e32 v221, v200
	v_mov_b32_e32 v222, v176
.LBB13_1336:
	ds_read_b128 v[82:85], v201
	ds_read_b128 v[90:93], v201 offset:1024
	ds_read_b128 v[94:97], v201 offset:2048
	ds_read_b128 v[102:105], v201 offset:3072
	ds_read_b128 v[158:161], v202
	ds_read_b128 v[162:165], v202 offset:1024
	ds_read_b128 v[166:169], v202 offset:2048
	ds_read_b128 v[170:173], v202 offset:3072
	s_add_u32 s8, s2, 0x100
	s_addc_u32 s9, s3, 0
	s_cmp_eq_u32 s82, 12
	s_cselect_b32 s58, s78, s8
	s_cselect_b32 s59, s47, s9
	s_cselect_b32 s12, s79, s80
	s_cselect_b32 s13, s49, s81
	s_add_u32 s10, s58, 0x80
	s_addc_u32 s11, s59, 0
	s_add_u32 s2, s2, 0x40080
	s_addc_u32 s3, s3, 0
	s_add_i32 m0, s57, 0xc000
	ds_read_b128 v[180:183], v203
	ds_read_b128 v[184:187], v203 offset:1024
	ds_read_b128 v[188:191], v203 offset:2048
	ds_read_b128 v[192:195], v203 offset:3072
	ds_read_b128 v[204:207], v203 offset:4096
	ds_read_b128 v[208:211], v203 offset:5120
	ds_read_b128 v[212:215], v203 offset:6144
	ds_read_b128 v[216:219], v203 offset:7168
	s_nop 0
	global_load_lds_dwordx4 v220, s[2:3]
	s_add_i32 m0, s57, 0xe000
	s_nop 0
	global_load_lds_dwordx4 v222, s[2:3]
	s_waitcnt vmcnt(8)
	s_waitcnt lgkmcnt(0)
	s_barrier
; #define PG8_STAGE(bufoff, gbase, voff) do { const char* gb_ = (const char*)(gbase); asm volatile("" : "+s"(gb_));     \
;         _Pragma("unroll") for (int _i = 0; _i < 2; ++_i) \
;         __builtin_amdgcn_global_load_lds((const unsigned*)(gb_ + (voff)[_i]), (PG8_LAS unsigned*)(lds + (bufoff) + ldsw + _i * 8192), 16, 0, 0); } while (0)
; #define PG8_LDA(dst, b, h) do { _Pragma("unroll") for (int m = 0; m < 4; ++m) _Pragma("unroll") for (int k = 0; k < 2; ++k) dst[m][k] = *(const PG8_LAS bf16x8*)(lds + PG8_SA(b, h) + aoff + m * 2048 + k * 1024); } while (0)
; #define PG8_LDB(dst, b, h) do { _Pragma("unroll") for (int n = 0; n < 2; ++n) _Pragma("unroll") for (int k = 0; k < 2; ++k) dst[n][k] = *(const PG8_LAS bf16x8*)(lds + PG8_SB(b, h) + boff + n * 2048 + k * 1024); } while (0)
; #define PG8_MMA(ai, bj, At, Bt) do { __builtin_amdgcn_s_setprio(1); _Pragma("unroll") for (int m = 0; m < 4; ++m) _Pragma("unroll") for (int n = 0; n < 2; ++n) _Pragma("unroll") for (int k = 0; k < 2; ++k) \
;         acc[ai][bj][m][n] = __builtin_amdgcn_mfma_f32_16x16x32_bf16(Bt[n][k], At[m][k], acc[ai][bj][m][n], 0, 0, 0); __builtin_amdgcn_s_setprio(0); } while (0)
; #define PG8_WAIT_V(n) asm volatile("s_waitcnt vmcnt(" #n ")" ::: "memory")
; #define PG8_WAIT_L(n) asm volatile("s_waitcnt lgkmcnt(" #n ")" ::: "memory")
; #define PG8_BAR __builtin_amdgcn_s_barrier()
; #define PG8_SCHED __builtin_amdgcn_sched_barrier(0)
; template <class Epi, class Sched, bool ALIGN_EPI = false, bool SP2 = false>
; __device__ __forceinline__ void gemm_phase(PG8_LAS unsigned char* lds, const Gemm g, const Sched& S, const Epi& E, int wid0) {
;     ...
;             PG8_LDB(B0, 0, 0); PG8_LDB(B1, 0, 1); PG8_SCHED; PG8_LDA(At, 0, 0); PG8_STAGE(PG8_SA(1, 1), a1 + hstepA, vA_);
;             PG8_WAIT_V(8); PG8_WAIT_L(0); PG8_BAR; PG8_MMA(0, 0, At, B0); PG8_MMA(0, 1, At, B1); PG8_BAR; PG8_SCHED;
;             PG8_LDA(At, 0, 1); PG8_STAGE(PG8_SB(0, 0), b2, vB_); PG8_STAGE(PG8_SB(0, 1), b2 + hstep, vB_); PG8_STAGE(PG8_SA(0, 0), a2, vA_);
;             PG8_WAIT_V(8); PG8_WAIT_L(0); PG8_BAR; PG8_MMA(1, 0, At, B0); PG8_MMA(1, 1, At, B1); PG8_BAR; PG8_SCHED;
	s_setprio 1
	s_waitcnt lgkmcnt(0)
	v_mfma_f32_16x16x32_bf16 v[154:157], v[82:85], v[180:183], v[154:157]
	v_mfma_f32_16x16x32_bf16 v[150:153], v[94:97], v[180:183], v[150:153]
	v_mfma_f32_16x16x32_bf16 v[138:141], v[82:85], v[188:191], v[138:141]
	v_mfma_f32_16x16x32_bf16 v[134:137], v[94:97], v[188:191], v[134:137]
	v_mfma_f32_16x16x32_bf16 v[122:125], v[82:85], v[204:207], v[122:125]
	v_mfma_f32_16x16x32_bf16 v[118:121], v[94:97], v[204:207], v[118:121]
	v_mfma_f32_16x16x32_bf16 v[106:109], v[82:85], v[212:215], v[106:109]
	v_mfma_f32_16x16x32_bf16 v[98:101], v[94:97], v[212:215], v[98:101]
	v_mfma_f32_16x16x32_bf16 v[154:157], v[90:93], v[184:187], v[154:157]
	v_mfma_f32_16x16x32_bf16 v[150:153], v[102:105], v[184:187], v[150:153]
	v_mfma_f32_16x16x32_bf16 v[138:141], v[90:93], v[192:195], v[138:141]
	v_mfma_f32_16x16x32_bf16 v[134:137], v[102:105], v[192:195], v[134:137]
	v_mfma_f32_16x16x32_bf16 v[122:125], v[90:93], v[208:211], v[122:125]
	v_mfma_f32_16x16x32_bf16 v[118:121], v[102:105], v[208:211], v[118:121]
	v_mfma_f32_16x16x32_bf16 v[106:109], v[90:93], v[216:219], v[106:109]
	v_mfma_f32_16x16x32_bf16 v[98:101], v[102:105], v[216:219], v[98:101]
	s_setprio 0
	s_setprio 1
	v_mfma_f32_16x16x32_bf16 v[146:149], v[158:161], v[180:183], v[146:149]
	v_mfma_f32_16x16x32_bf16 v[142:145], v[166:169], v[180:183], v[142:145]
	v_mfma_f32_16x16x32_bf16 v[130:133], v[158:161], v[188:191], v[130:133]
	v_mfma_f32_16x16x32_bf16 v[126:129], v[166:169], v[188:191], v[126:129]
	v_mfma_f32_16x16x32_bf16 v[114:117], v[158:161], v[204:207], v[114:117]
	v_mfma_f32_16x16x32_bf16 v[110:113], v[166:169], v[204:207], v[110:113]
	v_mfma_f32_16x16x32_bf16 v[86:89], v[158:161], v[212:215], v[86:89]
	v_mfma_f32_16x16x32_bf16 v[78:81], v[166:169], v[212:215], v[78:81]
	v_mfma_f32_16x16x32_bf16 v[146:149], v[162:165], v[184:187], v[146:149]
	v_mfma_f32_16x16x32_bf16 v[142:145], v[170:173], v[184:187], v[142:145]
	v_mfma_f32_16x16x32_bf16 v[130:133], v[162:165], v[192:195], v[130:133]
	v_mfma_f32_16x16x32_bf16 v[126:129], v[170:173], v[192:195], v[126:129]
	v_mfma_f32_16x16x32_bf16 v[114:117], v[162:165], v[208:211], v[114:117]
	v_mfma_f32_16x16x32_bf16 v[110:113], v[170:173], v[208:211], v[110:113]
	v_mfma_f32_16x16x32_bf16 v[86:89], v[162:165], v[216:219], v[86:89]
	v_mfma_f32_16x16x32_bf16 v[78:81], v[170:173], v[216:219], v[78:81]
	s_setprio 0
	s_barrier
	s_add_i32 s83, s75, s55
	s_mov_b64 s[2:3], s[12:13]
	s_mov_b32 m0, s83
	ds_read_b128 v[180:183], v203 offset:16384
	ds_read_b128 v[184:187], v203 offset:17408
	ds_read_b128 v[188:191], v203 offset:18432
	ds_read_b128 v[192:195], v203 offset:19456
	ds_read_b128 v[204:207], v203 offset:20480
	ds_read_b128 v[208:211], v203 offset:21504
	ds_read_b128 v[212:215], v203 offset:22528
	ds_read_b128 v[216:219], v203 offset:23552
	s_nop 0
	global_load_lds_dwordx4 v221, s[2:3]
	s_add_i32 m0, s83, 0x2000
	s_nop 0
	global_load_lds_dwordx4 v8, s[2:3]
	s_add_u32 s2, s12, 0x40000
	s_addc_u32 s3, s13, 0
	s_add_i32 s83, s76, s55
	s_mov_b32 m0, s83
	s_nop 0
	global_load_lds_dwordx4 v221, s[2:3]
	s_add_i32 m0, s83, 0x2000
	s_nop 0
	global_load_lds_dwordx4 v8, s[2:3]
	s_mov_b64 s[2:3], s[58:59]
	s_mov_b32 m0, s57
	s_nop 0
	global_load_lds_dwordx4 v220, s[2:3]
	s_mov_b32 m0, s64
	s_nop 0
	global_load_lds_dwordx4 v222, s[2:3]
	s_waitcnt vmcnt(8)
	s_waitcnt lgkmcnt(0)
	s_barrier
	s_setprio 1
	s_waitcnt lgkmcnt(0)
	v_mfma_f32_16x16x32_bf16 v[74:77], v[82:85], v[180:183], v[74:77]
	v_mfma_f32_16x16x32_bf16 v[70:73], v[94:97], v[180:183], v[70:73]
	v_mfma_f32_16x16x32_bf16 v[58:61], v[82:85], v[188:191], v[58:61]
	v_mfma_f32_16x16x32_bf16 v[54:57], v[94:97], v[188:191], v[54:57]
	v_mfma_f32_16x16x32_bf16 v[42:45], v[82:85], v[204:207], v[42:45]
	v_mfma_f32_16x16x32_bf16 v[38:41], v[94:97], v[204:207], v[38:41]
	v_mfma_f32_16x16x32_bf16 v[26:29], v[82:85], v[212:215], v[26:29]
	v_mfma_f32_16x16x32_bf16 v[22:25], v[94:97], v[212:215], v[22:25]
	v_mfma_f32_16x16x32_bf16 v[74:77], v[90:93], v[184:187], v[74:77]
	v_mfma_f32_16x16x32_bf16 v[70:73], v[102:105], v[184:187], v[70:73]
	v_mfma_f32_16x16x32_bf16 v[58:61], v[90:93], v[192:195], v[58:61]
	v_mfma_f32_16x16x32_bf16 v[54:57], v[102:105], v[192:195], v[54:57]
	v_mfma_f32_16x16x32_bf16 v[42:45], v[90:93], v[208:211], v[42:45]
	v_mfma_f32_16x16x32_bf16 v[38:41], v[102:105], v[208:211], v[38:41]
	v_mfma_f32_16x16x32_bf16 v[26:29], v[90:93], v[216:219], v[26:29]
	v_mfma_f32_16x16x32_bf16 v[22:25], v[102:105], v[216:219], v[22:25]
	s_setprio 0
	s_setprio 1
	v_mfma_f32_16x16x32_bf16 v[66:69], v[158:161], v[180:183], v[66:69]
	v_mfma_f32_16x16x32_bf16 v[62:65], v[166:169], v[180:183], v[62:65]
	v_mfma_f32_16x16x32_bf16 v[50:53], v[158:161], v[188:191], v[50:53]
	v_mfma_f32_16x16x32_bf16 v[46:49], v[166:169], v[188:191], v[46:49]
	v_mfma_f32_16x16x32_bf16 v[34:37], v[158:161], v[204:207], v[34:37]
	v_mfma_f32_16x16x32_bf16 v[30:33], v[166:169], v[204:207], v[30:33]
	v_mfma_f32_16x16x32_bf16 v[18:21], v[158:161], v[212:215], v[18:21]
	v_mfma_f32_16x16x32_bf16 v[14:17], v[166:169], v[212:215], v[14:17]
	v_mfma_f32_16x16x32_bf16 v[66:69], v[162:165], v[184:187], v[66:69]
	v_mfma_f32_16x16x32_bf16 v[62:65], v[170:173], v[184:187], v[62:65]
	v_mfma_f32_16x16x32_bf16 v[50:53], v[162:165], v[192:195], v[50:53]
	v_mfma_f32_16x16x32_bf16 v[46:49], v[170:173], v[192:195], v[46:49]
	v_mfma_f32_16x16x32_bf16 v[34:37], v[162:165], v[208:211], v[34:37]
	v_mfma_f32_16x16x32_bf16 v[30:33], v[170:173], v[208:211], v[30:33]
	v_mfma_f32_16x16x32_bf16 v[18:21], v[162:165], v[216:219], v[18:21]
	v_mfma_f32_16x16x32_bf16 v[14:17], v[170:173], v[216:219], v[14:17]
	s_setprio 0
	s_barrier
; #define PG8_STAGE(bufoff, gbase, voff) do { const char* gb_ = (const char*)(gbase); asm volatile("" : "+s"(gb_));     \
;         _Pragma("unroll") for (int _i = 0; _i < 2; ++_i) \
;         __builtin_amdgcn_global_load_lds((const unsigned*)(gb_ + (voff)[_i]), (PG8_LAS unsigned*)(lds + (bufoff) + ldsw + _i * 8192), 16, 0, 0); } while (0)
; #define PG8_LDA(dst, b, h) do { _Pragma("unroll") for (int m = 0; m < 4; ++m) _Pragma("unroll") for (int k = 0; k < 2; ++k) dst[m][k] = *(const PG8_LAS bf16x8*)(lds + PG8_SA(b, h) + aoff + m * 2048 + k * 1024); } while (0)
; #define PG8_LDB(dst, b, h) do { _Pragma("unroll") for (int n = 0; n < 2; ++n) _Pragma("unroll") for (int k = 0; k < 2; ++k) dst[n][k] = *(const PG8_LAS bf16x8*)(lds + PG8_SB(b, h) + boff + n * 2048 + k * 1024); } while (0)
; #define PG8_MMA(ai, bj, At, Bt) do { __builtin_amdgcn_s_setprio(1); _Pragma("unroll") for (int m = 0; m < 4; ++m) _Pragma("unroll") for (int n = 0; n < 2; ++n) _Pragma("unroll") for (int k = 0; k < 2; ++k) \
;         acc[ai][bj][m][n] = __builtin_amdgcn_mfma_f32_16x16x32_bf16(Bt[n][k], At[m][k], acc[ai][bj][m][n], 0, 0, 0); __builtin_amdgcn_s_setprio(0); } while (0)
; #define PG8_WAIT_V(n) asm volatile("s_waitcnt vmcnt(" #n ")" ::: "memory")
; #define PG8_WAIT_L(n) asm volatile("s_waitcnt lgkmcnt(" #n ")" ::: "memory")
; #define PG8_BAR __builtin_amdgcn_s_barrier()
; #define PG8_SCHED __builtin_amdgcn_sched_barrier(0)
; template <class Epi, class Sched, bool ALIGN_EPI = false, bool SP2 = false>
; __device__ __forceinline__ void gemm_phase(PG8_LAS unsigned char* lds, const Gemm g, const Sched& S, const Epi& E, int wid0) {
;     ...
;             PG8_LDB(B0, 1, 0); PG8_LDB(B1, 1, 1); PG8_SCHED; PG8_LDA(At, 1, 0); PG8_STAGE(PG8_SA(0, 1), a2 + hstepA, vA_);
;             PG8_WAIT_V(8); PG8_WAIT_L(0); PG8_BAR; PG8_MMA(0, 0, At, B0); PG8_MMA(0, 1, At, B1); PG8_BAR; PG8_SCHED;
;             PG8_LDA(At, 1, 1); PG8_STAGE(PG8_SB(1, 0), b3, vB_); PG8_STAGE(PG8_SB(1, 1), b3 + hstep, vB_); PG8_STAGE(PG8_SA(1, 0), a3, vA_);
;             PG8_WAIT_V(8); PG8_WAIT_L(0); PG8_BAR; PG8_MMA(1, 0, At, B0); PG8_MMA(1, 1, At, B1); PG8_BAR; PG8_SCHED;
	s_add_i32 s83, 0, 0x18000
	s_add_i32 s84, 0, 0x1c000
	v_add_u32_e32 v102, s83, v175
	v_add_u32_e32 v170, s84, v175
	ds_read_b128 v[82:85], v102
	ds_read_b128 v[90:93], v102 offset:1024
	ds_read_b128 v[94:97], v102 offset:2048
	ds_read_b128 v[102:105], v102 offset:3072
	ds_read_b128 v[158:161], v170
	ds_read_b128 v[162:165], v170 offset:1024
	ds_read_b128 v[166:169], v170 offset:2048
	ds_read_b128 v[170:173], v170 offset:3072
	s_add_u32 s2, s58, 0x40000
	s_addc_u32 s3, s59, 0
	s_mov_b32 m0, s65
	ds_read_b128 v[180:183], v203 offset:32768
	ds_read_b128 v[184:187], v203 offset:33792
	ds_read_b128 v[188:191], v203 offset:34816
	ds_read_b128 v[192:195], v203 offset:35840
	ds_read_b128 v[204:207], v203 offset:36864
	ds_read_b128 v[208:211], v203 offset:37888
	ds_read_b128 v[212:215], v203 offset:38912
	ds_read_b128 v[216:219], v203 offset:39936
	s_nop 0
	global_load_lds_dwordx4 v220, s[2:3]
	s_mov_b32 m0, s66
	s_nop 0
	global_load_lds_dwordx4 v222, s[2:3]
	s_waitcnt vmcnt(8)
	s_waitcnt lgkmcnt(0)
	s_barrier
	s_setprio 1
	s_waitcnt lgkmcnt(0)
	v_mfma_f32_16x16x32_bf16 v[154:157], v[82:85], v[180:183], v[154:157]
	v_mfma_f32_16x16x32_bf16 v[150:153], v[94:97], v[180:183], v[150:153]
	v_mfma_f32_16x16x32_bf16 v[138:141], v[82:85], v[188:191], v[138:141]
	v_mfma_f32_16x16x32_bf16 v[134:137], v[94:97], v[188:191], v[134:137]
	v_mfma_f32_16x16x32_bf16 v[122:125], v[82:85], v[204:207], v[122:125]
	v_mfma_f32_16x16x32_bf16 v[118:121], v[94:97], v[204:207], v[118:121]
	v_mfma_f32_16x16x32_bf16 v[106:109], v[82:85], v[212:215], v[106:109]
	v_mfma_f32_16x16x32_bf16 v[98:101], v[94:97], v[212:215], v[98:101]
	v_mfma_f32_16x16x32_bf16 v[154:157], v[90:93], v[184:187], v[154:157]
	v_mfma_f32_16x16x32_bf16 v[150:153], v[102:105], v[184:187], v[150:153]
	v_mfma_f32_16x16x32_bf16 v[138:141], v[90:93], v[192:195], v[138:141]
	v_mfma_f32_16x16x32_bf16 v[134:137], v[102:105], v[192:195], v[134:137]
	v_mfma_f32_16x16x32_bf16 v[122:125], v[90:93], v[208:211], v[122:125]
	v_mfma_f32_16x16x32_bf16 v[118:121], v[102:105], v[208:211], v[118:121]
	v_mfma_f32_16x16x32_bf16 v[106:109], v[90:93], v[216:219], v[106:109]
	v_mfma_f32_16x16x32_bf16 v[98:101], v[102:105], v[216:219], v[98:101]
	s_setprio 0
	s_setprio 1
	v_mfma_f32_16x16x32_bf16 v[146:149], v[158:161], v[180:183], v[146:149]
	v_mfma_f32_16x16x32_bf16 v[142:145], v[166:169], v[180:183], v[142:145]
	v_mfma_f32_16x16x32_bf16 v[130:133], v[158:161], v[188:191], v[130:133]
	v_mfma_f32_16x16x32_bf16 v[126:129], v[166:169], v[188:191], v[126:129]
	v_mfma_f32_16x16x32_bf16 v[114:117], v[158:161], v[204:207], v[114:117]
	v_mfma_f32_16x16x32_bf16 v[110:113], v[166:169], v[204:207], v[110:113]
	v_mfma_f32_16x16x32_bf16 v[86:89], v[158:161], v[212:215], v[86:89]
	v_mfma_f32_16x16x32_bf16 v[78:81], v[166:169], v[212:215], v[78:81]
	v_mfma_f32_16x16x32_bf16 v[146:149], v[162:165], v[184:187], v[146:149]
	v_mfma_f32_16x16x32_bf16 v[142:145], v[170:173], v[184:187], v[142:145]
	v_mfma_f32_16x16x32_bf16 v[130:133], v[162:165], v[192:195], v[130:133]
	v_mfma_f32_16x16x32_bf16 v[126:129], v[170:173], v[192:195], v[126:129]
	v_mfma_f32_16x16x32_bf16 v[114:117], v[162:165], v[208:211], v[114:117]
	v_mfma_f32_16x16x32_bf16 v[110:113], v[170:173], v[208:211], v[110:113]
	v_mfma_f32_16x16x32_bf16 v[86:89], v[162:165], v[216:219], v[86:89]
	v_mfma_f32_16x16x32_bf16 v[78:81], v[170:173], v[216:219], v[78:81]
	s_setprio 0
	s_barrier
	s_add_u32 s2, s12, 0x80
	s_addc_u32 s3, s13, 0
	s_add_i32 s58, s83, s55
	s_mov_b32 m0, s58
	ds_read_b128 v[180:183], v203 offset:49152
	ds_read_b128 v[184:187], v203 offset:50176
	ds_read_b128 v[188:191], v203 offset:51200
	ds_read_b128 v[192:195], v203 offset:52224
	ds_read_b128 v[204:207], v203 offset:53248
	ds_read_b128 v[208:211], v203 offset:54272
	ds_read_b128 v[212:215], v203 offset:55296
	ds_read_b128 v[216:219], v203 offset:56320
	s_nop 0
	global_load_lds_dwordx4 v221, s[2:3]
	s_add_i32 m0, s58, 0x2000
	s_nop 0
	global_load_lds_dwordx4 v8, s[2:3]
	s_add_u32 s2, s12, 0x40080
	s_addc_u32 s3, s13, 0
	s_add_i32 s12, s84, s55
	s_mov_b32 m0, s12
	s_nop 0
	global_load_lds_dwordx4 v221, s[2:3]
	s_add_i32 m0, s12, 0x2000
	s_nop 0
	global_load_lds_dwordx4 v8, s[2:3]
	s_mov_b32 m0, s69
	s_nop 0
	global_load_lds_dwordx4 v220, s[10:11]
	s_mov_b32 m0, s70
	s_nop 0
	global_load_lds_dwordx4 v222, s[10:11]
	s_waitcnt vmcnt(8)
	s_waitcnt lgkmcnt(0)
	s_barrier
	s_setprio 1
	s_waitcnt lgkmcnt(0)
	v_mfma_f32_16x16x32_bf16 v[74:77], v[82:85], v[180:183], v[74:77]
	v_mfma_f32_16x16x32_bf16 v[70:73], v[94:97], v[180:183], v[70:73]
	v_mfma_f32_16x16x32_bf16 v[58:61], v[82:85], v[188:191], v[58:61]
	v_mfma_f32_16x16x32_bf16 v[54:57], v[94:97], v[188:191], v[54:57]
	v_mfma_f32_16x16x32_bf16 v[42:45], v[82:85], v[204:207], v[42:45]
	v_mfma_f32_16x16x32_bf16 v[38:41], v[94:97], v[204:207], v[38:41]
	v_mfma_f32_16x16x32_bf16 v[26:29], v[82:85], v[212:215], v[26:29]
	v_mfma_f32_16x16x32_bf16 v[22:25], v[94:97], v[212:215], v[22:25]
	v_mfma_f32_16x16x32_bf16 v[74:77], v[90:93], v[184:187], v[74:77]
	v_mfma_f32_16x16x32_bf16 v[70:73], v[102:105], v[184:187], v[70:73]
	v_mfma_f32_16x16x32_bf16 v[58:61], v[90:93], v[192:195], v[58:61]
	v_mfma_f32_16x16x32_bf16 v[54:57], v[102:105], v[192:195], v[54:57]
	v_mfma_f32_16x16x32_bf16 v[42:45], v[90:93], v[208:211], v[42:45]
	v_mfma_f32_16x16x32_bf16 v[38:41], v[102:105], v[208:211], v[38:41]
	v_mfma_f32_16x16x32_bf16 v[26:29], v[90:93], v[216:219], v[26:29]
	v_mfma_f32_16x16x32_bf16 v[22:25], v[102:105], v[216:219], v[22:25]
	s_setprio 0
	s_setprio 1
	v_mfma_f32_16x16x32_bf16 v[66:69], v[158:161], v[180:183], v[66:69]
	v_mfma_f32_16x16x32_bf16 v[62:65], v[166:169], v[180:183], v[62:65]
	v_mfma_f32_16x16x32_bf16 v[50:53], v[158:161], v[188:191], v[50:53]
	v_mfma_f32_16x16x32_bf16 v[46:49], v[166:169], v[188:191], v[46:49]
	v_mfma_f32_16x16x32_bf16 v[34:37], v[158:161], v[204:207], v[34:37]
	v_mfma_f32_16x16x32_bf16 v[30:33], v[166:169], v[204:207], v[30:33]
	v_mfma_f32_16x16x32_bf16 v[18:21], v[158:161], v[212:215], v[18:21]
	v_mfma_f32_16x16x32_bf16 v[14:17], v[166:169], v[212:215], v[14:17]
	v_mfma_f32_16x16x32_bf16 v[66:69], v[162:165], v[184:187], v[66:69]
	v_mfma_f32_16x16x32_bf16 v[62:65], v[170:173], v[184:187], v[62:65]
	v_mfma_f32_16x16x32_bf16 v[50:53], v[162:165], v[192:195], v[50:53]
	v_mfma_f32_16x16x32_bf16 v[46:49], v[170:173], v[192:195], v[46:49]
	s_add_i32 s82, s82, 2
	s_add_u32 s80, s80, 0x100
	s_addc_u32 s81, s81, 0
	s_cmp_gt_u32 s82, 13
	s_mov_b64 s[2:3], s[8:9]
	v_mov_b32_e32 v8, v178
	v_mov_b32_e32 v220, v174
	v_mov_b32_e32 v221, v200
	v_mov_b32_e32 v222, v176
	v_mfma_f32_16x16x32_bf16 v[34:37], v[162:165], v[208:211], v[34:37]
	v_mfma_f32_16x16x32_bf16 v[30:33], v[170:173], v[208:211], v[30:33]
	v_mfma_f32_16x16x32_bf16 v[18:21], v[162:165], v[216:219], v[18:21]
	v_mfma_f32_16x16x32_bf16 v[14:17], v[170:173], v[216:219], v[14:17]
	s_setprio 0
	s_barrier
	s_cbranch_scc0 .LBB13_1336
	s_and_b64 vcc, exec, s[42:43]
	s_cbranch_vccz .LBB13_1339
	s_barrier

;     __device__ float mid(int row) const { return rg(row) / ra(row); }
;     __device__ __forceinline__ bool next(int i, Unit& u) const { return map(rank + i * nloc, u); }
;     __device__ __forceinline__ bool next(int i, Unit& u) const { if (i >= __builtin_amdgcn_readfirstlane(tab[0])) return false; u.pm = __builtin_amdgcn_readfirstlane(tab[1 + 2 * i]); u.pn = __builtin_amdgcn_readfirstlane(tab[2 + 2 * i]); return true; }
; #define PG8_STAGE(bufoff, gbase, voff) do { const char* gb_ = (const char*)(gbase); asm volatile("" : "+s"(gb_));     \
;         _Pragma("unroll") for (int _i = 0; _i < 2; ++_i) \
;         __builtin_amdgcn_global_load_lds((const unsigned*)(gb_ + (voff)[_i]), (PG8_LAS unsigned*)(lds + (bufoff) + ldsw + _i * 8192), 16, 0, 0); } while (0)
; #define PG8_LDA(dst, b, h) do { _Pragma("unroll") for (int m = 0; m < 4; ++m) _Pragma("unroll") for (int k = 0; k < 2; ++k) dst[m][k] = *(const PG8_LAS bf16x8*)(lds + PG8_SA(b, h) + aoff + m * 2048 + k * 1024); } while (0)
; template <class Epi, class Sched, bool ALIGN_EPI = false, bool SP2 = false>
; __device__ __forceinline__ void gemm_phase(PG8_LAS unsigned char* lds, const Gemm g, const Sched& S, const Epi& E, int wid0) {
;     ...
;         const bool has_next = S.next(ui + 1, nxt); nxt.ui = ui + 1;
;         if constexpr (Epi::HAS_PRE) E.pre_finish(lds, cur, tid, pq0, pq1, pq2);
;         const char* nA = has_next ? (const char*)g.A + (size_t)nxt.pm * tstepA : cA; const char* nB = has_next ? (const char*)g.Bt + (size_t)nxt.pn * tstep : cB;
; #pragma nounroll
;         for (int t = 0; t < nt; t += 2) {
;             const bool last = (t == nt - 2);
;             const char* a1 = cA + (size_t)(t + 1) * kstep;
;             const char* a2 = last ? nA : cA + (size_t)(t + 2) * kstep; const char* b2 = last ? nB : cB + (size_t)(t + 2) * kstep;
;             const char* a3 = a2 + kstep; const char* b3 = b2 + kstep;
;             if (last && has_next) S.a_ready(nxt);
;             if constexpr (Epi::HAS_MID) { if (t == Epi::MID_T) E.mid(acc, cur, wr, fr); }
;             unsigned vA_[2] = {voffA[0], voffA[1]}, vB_[2] = {voffB[0], voffB[1]};
;             asm volatile("" : "+v"(vA_[0]), "+v"(vA_[1]), "+v"(vB_[0]), "+v"(vB_[1]));
;             if constexpr (SP2) {
;             PG8_LDB(B0, 0, 0); PG8_LDB(B1, 0, 1); PG8_SCHED; PG8_LDA(At, 0, 0); PG8_STAGE(PG8_SA(1, 1), a1 + hstepA, vA_);
.LBB13_2162:
	s_ashr_i32 s11, s10, 31
	s_lshl_b64 s[14:15], s[10:11], 21
	s_add_u32 s14, s36, s14
	s_addc_u32 s15, s37, s15
	s_and_b64 s[18:19], s[16:17], exec
	s_cselect_b32 s11, s15, s25
	s_cselect_b32 s49, s14, s24
	s_ashr_i32 s13, s12, 31
	s_lshl_b64 s[18:19], s[12:13], 21
	s_add_u32 s18, s38, s18
	s_addc_u32 s19, s39, s19
	s_and_b64 s[28:29], s[16:17], exec
	s_cselect_b32 s13, s19, s27
	s_cselect_b32 s50, s18, s26
	s_add_u32 s51, s26, 0x100
	v_mov_b32_e32 v0, 0
	s_addc_u32 s52, s27, 0
	s_mov_b32 s53, -2
	v_mov_b32_e32 v1, v0
	v_mov_b32_e32 v2, v0
	v_mov_b32_e32 v3, v0
	v_mov_b32_e32 v4, v0
	v_mov_b32_e32 v5, v0
	v_mov_b32_e32 v6, v0
	v_mov_b32_e32 v7, v0
	v_mov_b32_e32 v8, v0
	v_mov_b32_e32 v9, v0
	v_mov_b32_e32 v10, v0
	v_mov_b32_e32 v11, v0
	v_mov_b32_e32 v12, v0
	v_mov_b32_e32 v13, v0
	v_mov_b32_e32 v14, v0
	v_mov_b32_e32 v15, v0
	v_mov_b32_e32 v16, v0
	v_mov_b32_e32 v17, v0
	v_mov_b32_e32 v18, v0
	v_mov_b32_e32 v19, v0
	v_mov_b32_e32 v20, v0
	v_mov_b32_e32 v21, v0
	v_mov_b32_e32 v22, v0
	v_mov_b32_e32 v23, v0
	v_mov_b32_e32 v24, v0
	v_mov_b32_e32 v25, v0
	v_mov_b32_e32 v26, v0
	v_mov_b32_e32 v27, v0
	v_mov_b32_e32 v28, v0
	v_mov_b32_e32 v29, v0
	v_mov_b32_e32 v30, v0
	v_mov_b32_e32 v31, v0
	v_mov_b32_e32 v64, v0
	v_mov_b32_e32 v65, v0
	v_mov_b32_e32 v66, v0
	v_mov_b32_e32 v67, v0
	v_mov_b32_e32 v68, v0
	v_mov_b32_e32 v69, v0
	v_mov_b32_e32 v70, v0
	v_mov_b32_e32 v71, v0
	v_mov_b32_e32 v72, v0
	v_mov_b32_e32 v73, v0
	v_mov_b32_e32 v74, v0
	v_mov_b32_e32 v75, v0
	v_mov_b32_e32 v76, v0
	v_mov_b32_e32 v77, v0
	v_mov_b32_e32 v78, v0
	v_mov_b32_e32 v79, v0
	v_mov_b32_e32 v80, v0
	v_mov_b32_e32 v81, v0
	v_mov_b32_e32 v82, v0
	v_mov_b32_e32 v83, v0
	v_mov_b32_e32 v84, v0
	v_mov_b32_e32 v85, v0
	v_mov_b32_e32 v86, v0
	v_mov_b32_e32 v87, v0
	v_mov_b32_e32 v88, v0
	v_mov_b32_e32 v89, v0
	v_mov_b32_e32 v90, v0
	v_mov_b32_e32 v91, v0
	v_mov_b32_e32 v92, v0
	v_mov_b32_e32 v93, v0
	v_mov_b32_e32 v94, v0
	v_mov_b32_e32 v95, v0
	v_mov_b32_e32 v32, v0
	v_mov_b32_e32 v33, v0
	v_mov_b32_e32 v34, v0
	v_mov_b32_e32 v35, v0
	v_mov_b32_e32 v36, v0
	v_mov_b32_e32 v37, v0
	v_mov_b32_e32 v38, v0
	v_mov_b32_e32 v39, v0
	v_mov_b32_e32 v40, v0
	v_mov_b32_e32 v41, v0
	v_mov_b32_e32 v42, v0
	v_mov_b32_e32 v43, v0
	v_mov_b32_e32 v44, v0
	v_mov_b32_e32 v45, v0
	v_mov_b32_e32 v46, v0
	v_mov_b32_e32 v47, v0
	v_mov_b32_e32 v48, v0
	v_mov_b32_e32 v49, v0
	v_mov_b32_e32 v50, v0
	v_mov_b32_e32 v51, v0
	v_mov_b32_e32 v52, v0
	v_mov_b32_e32 v53, v0
	v_mov_b32_e32 v54, v0
	v_mov_b32_e32 v55, v0
	v_mov_b32_e32 v56, v0
	v_mov_b32_e32 v57, v0
	v_mov_b32_e32 v58, v0
	v_mov_b32_e32 v59, v0
	v_mov_b32_e32 v60, v0
	v_mov_b32_e32 v61, v0
	v_mov_b32_e32 v62, v0
	v_mov_b32_e32 v63, v0
	v_mov_b32_e32 v96, v0
	v_mov_b32_e32 v97, v0
	v_mov_b32_e32 v98, v0
	v_mov_b32_e32 v99, v0
	v_mov_b32_e32 v100, v0
	v_mov_b32_e32 v101, v0
	v_mov_b32_e32 v102, v0
	v_mov_b32_e32 v103, v0
	v_mov_b32_e32 v104, v0
	v_mov_b32_e32 v105, v0
	v_mov_b32_e32 v106, v0
	v_mov_b32_e32 v107, v0
	v_mov_b32_e32 v108, v0
	v_mov_b32_e32 v109, v0
	v_mov_b32_e32 v110, v0
	v_mov_b32_e32 v111, v0
	v_mov_b32_e32 v112, v0
	v_mov_b32_e32 v113, v0
	v_mov_b32_e32 v114, v0
	v_mov_b32_e32 v115, v0
	v_mov_b32_e32 v116, v0
	v_mov_b32_e32 v117, v0
	v_mov_b32_e32 v118, v0
	v_mov_b32_e32 v119, v0
	v_mov_b32_e32 v120, v0
	v_mov_b32_e32 v121, v0
	v_mov_b32_e32 v122, v0
	v_mov_b32_e32 v123, v0
	v_mov_b32_e32 v124, v0
	v_mov_b32_e32 v125, v0
	v_mov_b32_e32 v126, v0
	v_mov_b32_e32 v127, v0
	v_mov_b32_e32 v202, v150
	v_mov_b32_e32 v203, v152
	v_mov_b32_e32 v204, v154
	v_mov_b32_e32 v205, v148
.LBB13_2163:
	ds_read_b128 v[128:131], v153
	ds_read_b128 v[132:135], v153 offset:1024
	ds_read_b128 v[136:139], v153 offset:2048
	ds_read_b128 v[140:143], v153 offset:3072
	ds_read_b128 v[144:147], v155
	ds_read_b128 v[158:161], v155 offset:1024
	ds_read_b128 v[162:165], v155 offset:2048
	ds_read_b128 v[166:169], v155 offset:3072
	s_add_u32 s26, s24, 0x100
	s_addc_u32 s27, s25, 0
	s_cmp_eq_u32 s53, 60
	s_cselect_b32 s34, s49, s26
	s_cselect_b32 s35, s11, s27
	s_cselect_b32 s30, s50, s51
	s_cselect_b32 s31, s13, s52
	s_add_u32 s28, s34, 0x80
	s_addc_u32 s29, s35, 0
	s_add_u32 s24, s24, 0x100080
	s_addc_u32 s25, s25, 0
	s_add_i32 m0, s21, 0xc000
	ds_read_b128 v[170:173], v156
	ds_read_b128 v[174:177], v156 offset:1024
	ds_read_b128 v[178:181], v156 offset:2048
	ds_read_b128 v[182:185], v156 offset:3072
	ds_read_b128 v[186:189], v156 offset:4096
	ds_read_b128 v[190:193], v156 offset:5120
	ds_read_b128 v[194:197], v156 offset:6144
	ds_read_b128 v[198:201], v156 offset:7168
	s_nop 0
	global_load_lds_dwordx4 v205, s[24:25]
	s_add_i32 m0, s21, 0xe000
	s_nop 0
	global_load_lds_dwordx4 v203, s[24:25]
	s_waitcnt vmcnt(8)
	s_waitcnt lgkmcnt(0)
	s_barrier
; #define PG8_STAGE(bufoff, gbase, voff) do { const char* gb_ = (const char*)(gbase); asm volatile("" : "+s"(gb_));     \
;         _Pragma("unroll") for (int _i = 0; _i < 2; ++_i) \
;         __builtin_amdgcn_global_load_lds((const unsigned*)(gb_ + (voff)[_i]), (PG8_LAS unsigned*)(lds + (bufoff) + ldsw + _i * 8192), 16, 0, 0); } while (0)
; #define PG8_LDA(dst, b, h) do { _Pragma("unroll") for (int m = 0; m < 4; ++m) _Pragma("unroll") for (int k = 0; k < 2; ++k) dst[m][k] = *(const PG8_LAS bf16x8*)(lds + PG8_SA(b, h) + aoff + m * 2048 + k * 1024); } while (0)
; #define PG8_LDB(dst, b, h) do { _Pragma("unroll") for (int n = 0; n < 2; ++n) _Pragma("unroll") for (int k = 0; k < 2; ++k) dst[n][k] = *(const PG8_LAS bf16x8*)(lds + PG8_SB(b, h) + boff + n * 2048 + k * 1024); } while (0)
; #define PG8_MMA(ai, bj, At, Bt) do { __builtin_amdgcn_s_setprio(1); _Pragma("unroll") for (int m = 0; m < 4; ++m) _Pragma("unroll") for (int n = 0; n < 2; ++n) _Pragma("unroll") for (int k = 0; k < 2; ++k) \
;         acc[ai][bj][m][n] = __builtin_amdgcn_mfma_f32_16x16x32_bf16(Bt[n][k], At[m][k], acc[ai][bj][m][n], 0, 0, 0); __builtin_amdgcn_s_setprio(0); } while (0)
; #define PG8_WAIT_V(n) asm volatile("s_waitcnt vmcnt(" #n ")" ::: "memory")
; #define PG8_WAIT_L(n) asm volatile("s_waitcnt lgkmcnt(" #n ")" ::: "memory")
; #define PG8_BAR __builtin_amdgcn_s_barrier()
; #define PG8_SCHED __builtin_amdgcn_sched_barrier(0)
; template <class Epi, class Sched, bool ALIGN_EPI = false, bool SP2 = false>
; __device__ __forceinline__ void gemm_phase(PG8_LAS unsigned char* lds, const Gemm g, const Sched& S, const Epi& E, int wid0) {
;     ...
;             PG8_LDB(B0, 0, 0); PG8_LDB(B1, 0, 1); PG8_SCHED; PG8_LDA(At, 0, 0); PG8_STAGE(PG8_SA(1, 1), a1 + hstepA, vA_);
;             PG8_WAIT_V(8); PG8_WAIT_L(0); PG8_BAR; PG8_MMA(0, 0, At, B0); PG8_MMA(0, 1, At, B1); PG8_BAR; PG8_SCHED;
;             PG8_LDA(At, 0, 1); PG8_STAGE(PG8_SB(0, 0), b2, vB_); PG8_STAGE(PG8_SB(0, 1), b2 + hstep, vB_); PG8_STAGE(PG8_SA(0, 0), a2, vA_);
;             PG8_WAIT_V(8); PG8_WAIT_L(0); PG8_BAR; PG8_MMA(1, 0, At, B0); PG8_MMA(1, 1, At, B1); PG8_BAR; PG8_SCHED;
	s_setprio 1
	s_waitcnt lgkmcnt(0)
	v_mfma_f32_16x16x32_bf16 v[124:127], v[128:131], v[170:173], v[124:127]
	v_mfma_f32_16x16x32_bf16 v[120:123], v[136:139], v[170:173], v[120:123]
	v_mfma_f32_16x16x32_bf16 v[116:119], v[128:131], v[178:181], v[116:119]
	v_mfma_f32_16x16x32_bf16 v[112:115], v[136:139], v[178:181], v[112:115]
	v_mfma_f32_16x16x32_bf16 v[108:111], v[128:131], v[186:189], v[108:111]
	v_mfma_f32_16x16x32_bf16 v[104:107], v[136:139], v[186:189], v[104:107]
	v_mfma_f32_16x16x32_bf16 v[100:103], v[128:131], v[194:197], v[100:103]
	v_mfma_f32_16x16x32_bf16 v[96:99], v[136:139], v[194:197], v[96:99]
	v_mfma_f32_16x16x32_bf16 v[124:127], v[132:135], v[174:177], v[124:127]
	v_mfma_f32_16x16x32_bf16 v[120:123], v[140:143], v[174:177], v[120:123]
	v_mfma_f32_16x16x32_bf16 v[116:119], v[132:135], v[182:185], v[116:119]
	v_mfma_f32_16x16x32_bf16 v[112:115], v[140:143], v[182:185], v[112:115]
	v_mfma_f32_16x16x32_bf16 v[108:111], v[132:135], v[190:193], v[108:111]
	v_mfma_f32_16x16x32_bf16 v[104:107], v[140:143], v[190:193], v[104:107]
	v_mfma_f32_16x16x32_bf16 v[100:103], v[132:135], v[198:201], v[100:103]
	v_mfma_f32_16x16x32_bf16 v[96:99], v[140:143], v[198:201], v[96:99]
	s_setprio 0
	s_setprio 1
	v_mfma_f32_16x16x32_bf16 v[60:63], v[144:147], v[170:173], v[60:63]
	v_mfma_f32_16x16x32_bf16 v[56:59], v[162:165], v[170:173], v[56:59]
	v_mfma_f32_16x16x32_bf16 v[52:55], v[144:147], v[178:181], v[52:55]
	v_mfma_f32_16x16x32_bf16 v[48:51], v[162:165], v[178:181], v[48:51]
	v_mfma_f32_16x16x32_bf16 v[44:47], v[144:147], v[186:189], v[44:47]
	v_mfma_f32_16x16x32_bf16 v[40:43], v[162:165], v[186:189], v[40:43]
	v_mfma_f32_16x16x32_bf16 v[36:39], v[144:147], v[194:197], v[36:39]
	v_mfma_f32_16x16x32_bf16 v[32:35], v[162:165], v[194:197], v[32:35]
	v_mfma_f32_16x16x32_bf16 v[60:63], v[158:161], v[174:177], v[60:63]
	v_mfma_f32_16x16x32_bf16 v[56:59], v[166:169], v[174:177], v[56:59]
	v_mfma_f32_16x16x32_bf16 v[52:55], v[158:161], v[182:185], v[52:55]
	v_mfma_f32_16x16x32_bf16 v[48:51], v[166:169], v[182:185], v[48:51]
	v_mfma_f32_16x16x32_bf16 v[44:47], v[158:161], v[190:193], v[44:47]
	v_mfma_f32_16x16x32_bf16 v[40:43], v[166:169], v[190:193], v[40:43]
	v_mfma_f32_16x16x32_bf16 v[36:39], v[158:161], v[198:201], v[36:39]
	v_mfma_f32_16x16x32_bf16 v[32:35], v[166:169], v[198:201], v[32:35]
	s_setprio 0
	s_barrier
	s_add_i32 s54, s47, s33
	s_mov_b64 s[24:25], s[30:31]
	s_mov_b32 m0, s54
	ds_read_b128 v[170:173], v156 offset:16384
	ds_read_b128 v[174:177], v156 offset:17408
	ds_read_b128 v[178:181], v156 offset:18432
	ds_read_b128 v[182:185], v156 offset:19456
	ds_read_b128 v[186:189], v156 offset:20480
	ds_read_b128 v[190:193], v156 offset:21504
	ds_read_b128 v[194:197], v156 offset:22528
	ds_read_b128 v[198:201], v156 offset:23552
	s_nop 0
	global_load_lds_dwordx4 v202, s[24:25]
	s_add_i32 m0, s54, 0x2000
	s_nop 0
	global_load_lds_dwordx4 v204, s[24:25]
	s_add_u32 s24, s30, 0x100000
	s_addc_u32 s25, s31, 0
	s_add_i32 s54, s48, s33
	s_mov_b32 m0, s54
	s_nop 0
	global_load_lds_dwordx4 v202, s[24:25]
	s_add_i32 m0, s54, 0x2000
	s_nop 0
	global_load_lds_dwordx4 v204, s[24:25]
	s_mov_b64 s[24:25], s[34:35]
	s_mov_b32 m0, s21
	s_nop 0
	global_load_lds_dwordx4 v205, s[24:25]
	s_mov_b32 m0, s23
	s_nop 0
	global_load_lds_dwordx4 v203, s[24:25]
	s_waitcnt vmcnt(8)
	s_waitcnt lgkmcnt(0)
	s_barrier
	s_setprio 1
	s_waitcnt lgkmcnt(0)
	v_mfma_f32_16x16x32_bf16 v[92:95], v[128:131], v[170:173], v[92:95]
	v_mfma_f32_16x16x32_bf16 v[88:91], v[136:139], v[170:173], v[88:91]
	v_mfma_f32_16x16x32_bf16 v[84:87], v[128:131], v[178:181], v[84:87]
	v_mfma_f32_16x16x32_bf16 v[80:83], v[136:139], v[178:181], v[80:83]
	v_mfma_f32_16x16x32_bf16 v[76:79], v[128:131], v[186:189], v[76:79]
	v_mfma_f32_16x16x32_bf16 v[72:75], v[136:139], v[186:189], v[72:75]
	v_mfma_f32_16x16x32_bf16 v[68:71], v[128:131], v[194:197], v[68:71]
	v_mfma_f32_16x16x32_bf16 v[64:67], v[136:139], v[194:197], v[64:67]
	v_mfma_f32_16x16x32_bf16 v[92:95], v[132:135], v[174:177], v[92:95]
	v_mfma_f32_16x16x32_bf16 v[88:91], v[140:143], v[174:177], v[88:91]
	v_mfma_f32_16x16x32_bf16 v[84:87], v[132:135], v[182:185], v[84:87]
	v_mfma_f32_16x16x32_bf16 v[80:83], v[140:143], v[182:185], v[80:83]
	v_mfma_f32_16x16x32_bf16 v[76:79], v[132:135], v[190:193], v[76:79]
	v_mfma_f32_16x16x32_bf16 v[72:75], v[140:143], v[190:193], v[72:75]
	v_mfma_f32_16x16x32_bf16 v[68:71], v[132:135], v[198:201], v[68:71]
	v_mfma_f32_16x16x32_bf16 v[64:67], v[140:143], v[198:201], v[64:67]
	s_setprio 0
	s_setprio 1
	v_mfma_f32_16x16x32_bf16 v[28:31], v[144:147], v[170:173], v[28:31]
	v_mfma_f32_16x16x32_bf16 v[24:27], v[162:165], v[170:173], v[24:27]
	v_mfma_f32_16x16x32_bf16 v[20:23], v[144:147], v[178:181], v[20:23]
	v_mfma_f32_16x16x32_bf16 v[16:19], v[162:165], v[178:181], v[16:19]
	v_mfma_f32_16x16x32_bf16 v[12:15], v[144:147], v[186:189], v[12:15]
	v_mfma_f32_16x16x32_bf16 v[8:11], v[162:165], v[186:189], v[8:11]
	v_mfma_f32_16x16x32_bf16 v[4:7], v[144:147], v[194:197], v[4:7]
	v_mfma_f32_16x16x32_bf16 v[0:3], v[162:165], v[194:197], v[0:3]
	v_mfma_f32_16x16x32_bf16 v[28:31], v[158:161], v[174:177], v[28:31]
	v_mfma_f32_16x16x32_bf16 v[24:27], v[166:169], v[174:177], v[24:27]
	v_mfma_f32_16x16x32_bf16 v[20:23], v[158:161], v[182:185], v[20:23]
	v_mfma_f32_16x16x32_bf16 v[16:19], v[166:169], v[182:185], v[16:19]
	v_mfma_f32_16x16x32_bf16 v[12:15], v[158:161], v[190:193], v[12:15]
	v_mfma_f32_16x16x32_bf16 v[8:11], v[166:169], v[190:193], v[8:11]
	v_mfma_f32_16x16x32_bf16 v[4:7], v[158:161], v[198:201], v[4:7]
	v_mfma_f32_16x16x32_bf16 v[0:3], v[166:169], v[198:201], v[0:3]
	s_setprio 0
	s_barrier
; #define PG8_STAGE(bufoff, gbase, voff) do { const char* gb_ = (const char*)(gbase); asm volatile("" : "+s"(gb_));     \
;         _Pragma("unroll") for (int _i = 0; _i < 2; ++_i) \
;         __builtin_amdgcn_global_load_lds((const unsigned*)(gb_ + (voff)[_i]), (PG8_LAS unsigned*)(lds + (bufoff) + ldsw + _i * 8192), 16, 0, 0); } while (0)
; #define PG8_LDA(dst, b, h) do { _Pragma("unroll") for (int m = 0; m < 4; ++m) _Pragma("unroll") for (int k = 0; k < 2; ++k) dst[m][k] = *(const PG8_LAS bf16x8*)(lds + PG8_SA(b, h) + aoff + m * 2048 + k * 1024); } while (0)
; #define PG8_LDB(dst, b, h) do { _Pragma("unroll") for (int n = 0; n < 2; ++n) _Pragma("unroll") for (int k = 0; k < 2; ++k) dst[n][k] = *(const PG8_LAS bf16x8*)(lds + PG8_SB(b, h) + boff + n * 2048 + k * 1024); } while (0)
; #define PG8_MMA(ai, bj, At, Bt) do { __builtin_amdgcn_s_setprio(1); _Pragma("unroll") for (int m = 0; m < 4; ++m) _Pragma("unroll") for (int n = 0; n < 2; ++n) _Pragma("unroll") for (int k = 0; k < 2; ++k) \
;         acc[ai][bj][m][n] = __builtin_amdgcn_mfma_f32_16x16x32_bf16(Bt[n][k], At[m][k], acc[ai][bj][m][n], 0, 0, 0); __builtin_amdgcn_s_setprio(0); } while (0)
; #define PG8_WAIT_V(n) asm volatile("s_waitcnt vmcnt(" #n ")" ::: "memory")
; #define PG8_WAIT_L(n) asm volatile("s_waitcnt lgkmcnt(" #n ")" ::: "memory")
; #define PG8_BAR __builtin_amdgcn_s_barrier()
; #define PG8_SCHED __builtin_amdgcn_sched_barrier(0)
; template <class Epi, class Sched, bool ALIGN_EPI = false, bool SP2 = false>
; __device__ __forceinline__ void gemm_phase(PG8_LAS unsigned char* lds, const Gemm g, const Sched& S, const Epi& E, int wid0) {
;     ...
;             PG8_LDB(B0, 1, 0); PG8_LDB(B1, 1, 1); PG8_SCHED; PG8_LDA(At, 1, 0); PG8_STAGE(PG8_SA(0, 1), a2 + hstepA, vA_);
;             PG8_WAIT_V(8); PG8_WAIT_L(0); PG8_BAR; PG8_MMA(0, 0, At, B0); PG8_MMA(0, 1, At, B1); PG8_BAR; PG8_SCHED;
;             PG8_LDA(At, 1, 1); PG8_STAGE(PG8_SB(1, 0), b3, vB_); PG8_STAGE(PG8_SB(1, 1), b3 + hstep, vB_); PG8_STAGE(PG8_SA(1, 0), a3, vA_);
;             PG8_WAIT_V(8); PG8_WAIT_L(0); PG8_BAR; PG8_MMA(1, 0, At, B0); PG8_MMA(1, 1, At, B1); PG8_BAR; PG8_SCHED;
	s_add_i32 s54, 0, 0x18000
	s_add_i32 s55, 0, 0x1c000
	v_add_u32_e32 v140, s54, v149
	v_add_u32_e32 v166, s55, v149
	ds_read_b128 v[128:131], v140
	ds_read_b128 v[132:135], v140 offset:1024
	ds_read_b128 v[136:139], v140 offset:2048
	ds_read_b128 v[140:143], v140 offset:3072
	ds_read_b128 v[144:147], v166
	ds_read_b128 v[158:161], v166 offset:1024
	ds_read_b128 v[162:165], v166 offset:2048
	ds_read_b128 v[166:169], v166 offset:3072
	s_add_u32 s24, s34, 0x100000
	s_addc_u32 s25, s35, 0
	s_mov_b32 m0, s40
	ds_read_b128 v[170:173], v156 offset:32768
	ds_read_b128 v[174:177], v156 offset:33792
	ds_read_b128 v[178:181], v156 offset:34816
	ds_read_b128 v[182:185], v156 offset:35840
	ds_read_b128 v[186:189], v156 offset:36864
	ds_read_b128 v[190:193], v156 offset:37888
	ds_read_b128 v[194:197], v156 offset:38912
	ds_read_b128 v[198:201], v156 offset:39936
	s_nop 0
	global_load_lds_dwordx4 v205, s[24:25]
	s_mov_b32 m0, s41
	s_nop 0
	global_load_lds_dwordx4 v203, s[24:25]
	s_waitcnt vmcnt(8)
	s_waitcnt lgkmcnt(0)
	s_barrier
	s_setprio 1
	s_waitcnt lgkmcnt(0)
	v_mfma_f32_16x16x32_bf16 v[124:127], v[128:131], v[170:173], v[124:127]
	v_mfma_f32_16x16x32_bf16 v[120:123], v[136:139], v[170:173], v[120:123]
	v_mfma_f32_16x16x32_bf16 v[116:119], v[128:131], v[178:181], v[116:119]
	v_mfma_f32_16x16x32_bf16 v[112:115], v[136:139], v[178:181], v[112:115]
	v_mfma_f32_16x16x32_bf16 v[108:111], v[128:131], v[186:189], v[108:111]
	v_mfma_f32_16x16x32_bf16 v[104:107], v[136:139], v[186:189], v[104:107]
	v_mfma_f32_16x16x32_bf16 v[100:103], v[128:131], v[194:197], v[100:103]
	v_mfma_f32_16x16x32_bf16 v[96:99], v[136:139], v[194:197], v[96:99]
	v_mfma_f32_16x16x32_bf16 v[124:127], v[132:135], v[174:177], v[124:127]
	v_mfma_f32_16x16x32_bf16 v[120:123], v[140:143], v[174:177], v[120:123]
	v_mfma_f32_16x16x32_bf16 v[116:119], v[132:135], v[182:185], v[116:119]
	v_mfma_f32_16x16x32_bf16 v[112:115], v[140:143], v[182:185], v[112:115]
	v_mfma_f32_16x16x32_bf16 v[108:111], v[132:135], v[190:193], v[108:111]
	v_mfma_f32_16x16x32_bf16 v[104:107], v[140:143], v[190:193], v[104:107]
	v_mfma_f32_16x16x32_bf16 v[100:103], v[132:135], v[198:201], v[100:103]
	v_mfma_f32_16x16x32_bf16 v[96:99], v[140:143], v[198:201], v[96:99]
	s_setprio 0
	s_setprio 1
	v_mfma_f32_16x16x32_bf16 v[60:63], v[144:147], v[170:173], v[60:63]
	v_mfma_f32_16x16x32_bf16 v[56:59], v[162:165], v[170:173], v[56:59]
	v_mfma_f32_16x16x32_bf16 v[52:55], v[144:147], v[178:181], v[52:55]
	v_mfma_f32_16x16x32_bf16 v[48:51], v[162:165], v[178:181], v[48:51]
	v_mfma_f32_16x16x32_bf16 v[44:47], v[144:147], v[186:189], v[44:47]
	v_mfma_f32_16x16x32_bf16 v[40:43], v[162:165], v[186:189], v[40:43]
	v_mfma_f32_16x16x32_bf16 v[36:39], v[144:147], v[194:197], v[36:39]
	v_mfma_f32_16x16x32_bf16 v[32:35], v[162:165], v[194:197], v[32:35]
	v_mfma_f32_16x16x32_bf16 v[60:63], v[158:161], v[174:177], v[60:63]
	v_mfma_f32_16x16x32_bf16 v[56:59], v[166:169], v[174:177], v[56:59]
	v_mfma_f32_16x16x32_bf16 v[52:55], v[158:161], v[182:185], v[52:55]
	v_mfma_f32_16x16x32_bf16 v[48:51], v[166:169], v[182:185], v[48:51]
	v_mfma_f32_16x16x32_bf16 v[44:47], v[158:161], v[190:193], v[44:47]
	v_mfma_f32_16x16x32_bf16 v[40:43], v[166:169], v[190:193], v[40:43]
	v_mfma_f32_16x16x32_bf16 v[36:39], v[158:161], v[198:201], v[36:39]
	v_mfma_f32_16x16x32_bf16 v[32:35], v[166:169], v[198:201], v[32:35]
	s_setprio 0
	s_barrier
	s_add_u32 s24, s30, 0x80
	s_addc_u32 s25, s31, 0
	s_add_i32 s34, s54, s33
	s_mov_b32 m0, s34
	ds_read_b128 v[170:173], v156 offset:49152
	ds_read_b128 v[174:177], v156 offset:50176
	ds_read_b128 v[178:181], v156 offset:51200
	ds_read_b128 v[182:185], v156 offset:52224
	ds_read_b128 v[186:189], v156 offset:53248
	ds_read_b128 v[190:193], v156 offset:54272
	ds_read_b128 v[194:197], v156 offset:55296
	ds_read_b128 v[198:201], v156 offset:56320
	s_nop 0
	global_load_lds_dwordx4 v202, s[24:25]
	s_add_i32 m0, s34, 0x2000
	s_nop 0
	global_load_lds_dwordx4 v204, s[24:25]
	s_add_u32 s24, s30, 0x100080
	s_addc_u32 s25, s31, 0
	s_add_i32 s30, s55, s33
	s_mov_b32 m0, s30
	s_nop 0
	global_load_lds_dwordx4 v202, s[24:25]
	s_add_i32 m0, s30, 0x2000
	s_nop 0
	global_load_lds_dwordx4 v204, s[24:25]
	s_mov_b32 m0, s45
	s_nop 0
	global_load_lds_dwordx4 v205, s[28:29]
	s_mov_b32 m0, s46
	s_nop 0
	global_load_lds_dwordx4 v203, s[28:29]
	s_waitcnt vmcnt(8)
	s_waitcnt lgkmcnt(0)
	s_barrier
	s_setprio 1
	s_waitcnt lgkmcnt(0)
	v_mfma_f32_16x16x32_bf16 v[92:95], v[128:131], v[170:173], v[92:95]
	v_mfma_f32_16x16x32_bf16 v[88:91], v[136:139], v[170:173], v[88:91]
	v_mfma_f32_16x16x32_bf16 v[84:87], v[128:131], v[178:181], v[84:87]
	v_mfma_f32_16x16x32_bf16 v[80:83], v[136:139], v[178:181], v[80:83]
	v_mfma_f32_16x16x32_bf16 v[76:79], v[128:131], v[186:189], v[76:79]
	v_mfma_f32_16x16x32_bf16 v[72:75], v[136:139], v[186:189], v[72:75]
	v_mfma_f32_16x16x32_bf16 v[68:71], v[128:131], v[194:197], v[68:71]
	v_mfma_f32_16x16x32_bf16 v[64:67], v[136:139], v[194:197], v[64:67]
	v_mfma_f32_16x16x32_bf16 v[92:95], v[132:135], v[174:177], v[92:95]
	v_mfma_f32_16x16x32_bf16 v[88:91], v[140:143], v[174:177], v[88:91]
	v_mfma_f32_16x16x32_bf16 v[84:87], v[132:135], v[182:185], v[84:87]
	v_mfma_f32_16x16x32_bf16 v[80:83], v[140:143], v[182:185], v[80:83]
	v_mfma_f32_16x16x32_bf16 v[76:79], v[132:135], v[190:193], v[76:79]
	v_mfma_f32_16x16x32_bf16 v[72:75], v[140:143], v[190:193], v[72:75]
	v_mfma_f32_16x16x32_bf16 v[68:71], v[132:135], v[198:201], v[68:71]
	v_mfma_f32_16x16x32_bf16 v[64:67], v[140:143], v[198:201], v[64:67]
	s_setprio 0
	s_setprio 1
	v_mfma_f32_16x16x32_bf16 v[28:31], v[144:147], v[170:173], v[28:31]
	v_mfma_f32_16x16x32_bf16 v[24:27], v[162:165], v[170:173], v[24:27]
	v_mfma_f32_16x16x32_bf16 v[20:23], v[144:147], v[178:181], v[20:23]
	v_mfma_f32_16x16x32_bf16 v[16:19], v[162:165], v[178:181], v[16:19]
	v_mfma_f32_16x16x32_bf16 v[12:15], v[144:147], v[186:189], v[12:15]
	v_mfma_f32_16x16x32_bf16 v[8:11], v[162:165], v[186:189], v[8:11]
	v_mfma_f32_16x16x32_bf16 v[4:7], v[144:147], v[194:197], v[4:7]
	v_mfma_f32_16x16x32_bf16 v[0:3], v[162:165], v[194:197], v[0:3]
	v_mfma_f32_16x16x32_bf16 v[28:31], v[158:161], v[174:177], v[28:31]
	v_mfma_f32_16x16x32_bf16 v[24:27], v[166:169], v[174:177], v[24:27]
	v_mfma_f32_16x16x32_bf16 v[20:23], v[158:161], v[182:185], v[20:23]
	v_mfma_f32_16x16x32_bf16 v[16:19], v[166:169], v[182:185], v[16:19]
	s_add_i32 s53, s53, 2
	s_add_u32 s51, s51, 0x100
	s_addc_u32 s52, s52, 0
	s_cmp_gt_u32 s53, 61
	s_mov_b64 s[24:25], s[26:27]
	v_mov_b32_e32 v202, v150
	v_mov_b32_e32 v203, v152
	v_mov_b32_e32 v204, v154
	v_mov_b32_e32 v205, v148
	v_mfma_f32_16x16x32_bf16 v[12:15], v[158:161], v[190:193], v[12:15]
	v_mfma_f32_16x16x32_bf16 v[8:11], v[166:169], v[190:193], v[8:11]
	v_mfma_f32_16x16x32_bf16 v[4:7], v[158:161], v[198:201], v[4:7]
	v_mfma_f32_16x16x32_bf16 v[0:3], v[166:169], v[198:201], v[0:3]
	s_setprio 0
	s_barrier
	s_cbranch_scc0 .LBB13_2163
	s_and_b64 vcc, exec, s[8:9]
	s_cbranch_vccz .LBB13_2166
	s_barrier
